# attn_a phase rewritten by hand: ping-pong (PV+QK | softmax) segments, waves 4-7 staggered
# speedup vs baseline: 1.0197x; 1.0197x over previous
; #define LAS __attribute__((address_space(3)))
; DI int otid() { int t = threadIdx.x; asm volatile("" : "+v"(t)); return t; }
; DI void phase_attn_a(const Params& p, LAS unsigned char* lds) {
;     const bf16_t* big = (const bf16_t*)(p.ws + ACT); bf16_t* y = (bf16_t*)(p.ws + HBUF); const float* tbg = (const float*)(p.ws + X_BIAS);
;     const int tid = otid(), wid = tid >> 6, lane = tid & 63, l32 = lane & 31, hh = lane >> 5;
;     constexpr int STG = 64 * (64 * 2 + 16 + 128 * 2 + 64);
;     float d0 = 0.f, d1 = 0.f;
;     for (int i = 0; i < 64; ++i) { d0 += p.in[5][i] * p.in[5][64 + i]; d1 += p.in[5][128 + i] * p.in[5][192 + i]; }
;     const float lam_init = 0.2f, lam = __expf(d0) - __expf(d1) + lam_init;
;     for (int pr = blockIdx.x; pr < 512; pr += gridDim.x) {
;         const int bi = pr & 255, bh = (gridDim.x == 256) ? (bi & 7) + 8 * (bi >> 6) + 32 * (pr >> 8) : pr >> 3, j = (gridDim.x == 256) ? (bi >> 3) & 7 : pr & 7, b = bh >> 4, h = bh & 15;
;         for (int half = 0; half < 2; ++half) {
;             const int qb = half ? 15 - j : j;
;             __syncthreads();
;             if (tid < 192) ((LAS float*)(lds + 2 * STG))[tid] = tbg[h * 192 + tid];
;             const size_t tok0 = (size_t)b * SEQ, tokq = tok0 + qb * 256 + wid * 32 + l32;
;             f32x16 Oa[4]; LAS unsigned* Op = (LAS unsigned*)(lds + 2 * STG + 1024) + wid * 2048 + lane;
;             attn_core<64, 8, 128, true, true>(lds, big + tokq * 8192 + h * 128, big + tok0 * 8192 + 2048 + h * 128, 8192, nullptr, 0, big + tok0 * 8192 + 4096 + h * 128, 8192, qb, wid, lane, nullptr, Oa);
.LBB0_225:
	s_or_b64 exec, exec, s[4:5]
	s_waitcnt vmcnt(0)
	v_mov_b32_e32 v179, v181
	s_waitcnt lgkmcnt(0)
	s_barrier
	s_load_dwordx2 s[4:5], s[0:1], 0xf0
	s_load_dwordx2 s[10:11], s[0:1], 0x30
	s_load_dwordx2 s[44:45], s[0:1], 0x28
	v_and_b32_e32 v191, 63, v181
	v_lshlrev_b32_e32 v186, 2, v191
	v_lshlrev_b32_e32 v192, 2, v181
	s_waitcnt lgkmcnt(0)
	global_load_dword v187, v186, s[44:45]
	global_load_dword v188, v186, s[44:45] offset:256
	global_load_dword v189, v186, s[44:45] offset:512
	global_load_dword v190, v186, s[44:45] offset:768
	v_cmp_gt_u32_e32 vcc, 128, v181
	s_and_saveexec_b64 s[66:67], vcc
	s_cbranch_execz .Laa_sgskip
	global_load_dword v193, v192, s[10:11]
	v_add_u32_e32 v195, 126976, v192
	s_waitcnt vmcnt(0)
	ds_write_b32 v195, v193
.Laa_sgskip:
	s_or_b64 exec, exec, s[66:67]
	s_add_u32 s6, s4, 0xbf00000
	s_addc_u32 s7, s5, 0
	s_add_u32 s8, s4, 0x7f00000
	s_addc_u32 s9, s5, 0
	s_add_u32 s64, s4, 0x1ff04000
	s_addc_u32 s65, s5, 0
	v_and_b32_e32 v185, 31, v191
	v_lshrrev_b32_e32 v194, 5, v191
	v_mul_u32_u24_e32 v172, 144, v185
	v_lshl_add_u32 v172, v194, 4, v172
	v_bfe_u32 v195, v191, 2, 2
	v_lshl_add_u32 v195, v194, 2, v195
	v_mul_u32_u24_e32 v173, 320, v195
	v_and_b32_e32 v195, 3, v191
	v_lshl_add_u32 v173, v195, 3, v173
	v_bfe_u32 v195, v191, 4, 1
	v_lshl_add_u32 v173, v195, 5, v173
	v_lshrrev_b32_e32 v195, 3, v181
	v_and_b32_e32 v196, 7, v181
	v_mul_u32_u24_e32 v174, 144, v195
	v_lshl_add_u32 v174, v196, 4, v174
	v_lshlrev_b32_e32 v176, 14, v195
	v_lshl_add_u32 v176, v196, 4, v176
	v_lshrrev_b32_e32 v195, 4, v181
	v_and_b32_e32 v196, 15, v181
	v_mul_u32_u24_e32 v175, 320, v195
	v_lshl_add_u32 v175, v196, 4, v175
	v_lshlrev_b32_e32 v177, 14, v195
	v_lshl_add_u32 v177, v196, 4, v177
	v_add_u32_e32 v182, 0x80000, v177
	v_lshlrev_b32_e32 v197, 14, v185
	v_lshl_add_u32 v198, v194, 3, v197
	v_lshl_add_u32 v197, v194, 4, v197
	v_lshlrev_b32_e32 v199, 12, v185
	v_lshl_add_u32 v199, v194, 3, v199
	v_lshrrev_b32_e32 v195, 6, v181
	v_lshlrev_b32_e32 v200, 13, v195
	v_lshl_add_u32 v200, v191, 2, v200
	v_add_u32_e32 v200, 60416, v200
	v_lshlrev_b32_e32 v201, 4, v194
	v_add_u32_e32 v201, 126976, v201
	v_lshlrev_b32_e32 v202, 2, v194
	v_sub_u32_e32 v202, v202, v185
	v_add_u32_e32 v202, 128, v202
	v_readfirstlane_b32 s26, v195
	s_waitcnt vmcnt(0)
	v_mul_f32_e32 v187, v187, v188
	v_mul_f32_e32 v189, v189, v190
	v_xor_b32_e32 v186, 32, v191
	v_lshlrev_b32_e32 v186, 2, v186
	ds_bpermute_b32 v188, v186, v187
	ds_bpermute_b32 v190, v186, v189
	s_waitcnt lgkmcnt(0)
	v_add_f32_e32 v187, v187, v188
	v_add_f32_e32 v189, v189, v190
	v_xor_b32_e32 v186, 16, v191
	v_lshlrev_b32_e32 v186, 2, v186
	ds_bpermute_b32 v188, v186, v187
	ds_bpermute_b32 v190, v186, v189
	s_waitcnt lgkmcnt(0)
	v_add_f32_e32 v187, v187, v188
	v_add_f32_e32 v189, v189, v190
	v_xor_b32_e32 v186, 8, v191
	v_lshlrev_b32_e32 v186, 2, v186
	ds_bpermute_b32 v188, v186, v187
	ds_bpermute_b32 v190, v186, v189
	s_waitcnt lgkmcnt(0)
	v_add_f32_e32 v187, v187, v188
	v_add_f32_e32 v189, v189, v190
	v_xor_b32_e32 v186, 4, v191
	v_lshlrev_b32_e32 v186, 2, v186
	ds_bpermute_b32 v188, v186, v187
	ds_bpermute_b32 v190, v186, v189
	s_waitcnt lgkmcnt(0)
	v_add_f32_e32 v187, v187, v188
	v_add_f32_e32 v189, v189, v190
	v_xor_b32_e32 v186, 2, v191
	v_lshlrev_b32_e32 v186, 2, v186
	ds_bpermute_b32 v188, v186, v187
	ds_bpermute_b32 v190, v186, v189
	s_waitcnt lgkmcnt(0)
	v_add_f32_e32 v187, v187, v188
	v_add_f32_e32 v189, v189, v190
	v_xor_b32_e32 v186, 1, v191
	v_lshlrev_b32_e32 v186, 2, v186
	ds_bpermute_b32 v188, v186, v187
	ds_bpermute_b32 v190, v186, v189
	s_waitcnt lgkmcnt(0)
	v_add_f32_e32 v187, v187, v188
	v_add_f32_e32 v189, v189, v190
	v_mul_f32_e32 v187, 0x3fb8aa3b, v187
	v_mul_f32_e32 v189, 0x3fb8aa3b, v189
	v_exp_f32_e32 v187, v187
	v_exp_f32_e32 v189, v189
	s_nop 1
	v_sub_f32_e32 v187, v187, v189
	v_add_f32_e32 v187, 0x3e4ccccd, v187
	s_nop 1
	v_readfirstlane_b32 s12, v187
	s_mov_b32 s14, s2
.Laa_unit:
	s_cmpk_gt_u32 s14, 0x1ff
	s_cbranch_scc1 .Laa_done
	s_cmp_eq_u32 s18, 0x100
	s_cbranch_scc0 .Laa_generic
	s_and_b32 s42, s14, 0xff
	s_and_b32 s58, s42, 7
	s_lshr_b32 s59, s42, 6
	s_lshl_b32 s59, s59, 3
	s_add_i32 s58, s58, s59
	s_lshr_b32 s59, s14, 8
	s_lshl_b32 s59, s59, 5
	s_add_i32 s58, s58, s59
	s_bfe_u32 s29, s42, 0x30003
	s_branch .Laa_decoded
.Laa_generic:
	s_lshr_b32 s58, s14, 3
	s_and_b32 s29, s14, 7
.Laa_decoded:
	s_lshr_b32 s28, s58, 4
	s_and_b32 s27, s58, 15
	s_barrier
	v_cmp_gt_u32_e32 vcc, 192, v181
	s_and_saveexec_b64 s[66:67], vcc
	s_cbranch_execz .Laa_btskip
	s_mul_i32 s58, s27, 768
	s_add_u32 s44, s64, s58
	s_addc_u32 s45, s65, 0
	global_load_dword v186, v192, s[44:45]
	s_waitcnt vmcnt(0)
	ds_write_b32 v192, v186 offset:59392
.Laa_btskip:
	s_or_b64 exec, exec, s[66:67]
	s_mov_b32 s15, 0
.Laa_half:
	s_sub_i32 s58, 15, s29
	s_cmp_eq_u32 s15, 0
	s_cselect_b32 s16, s29, s58
	s_lshl_b32 s17, s16, 2
	s_add_i32 s17, s17, 4
	s_lshl_b32 s43, s16, 8
	s_lshl_b32 s58, s26, 5
	s_add_i32 s43, s43, s58
	s_lshr_b32 s25, s43, 6
	v_subrev_u32_e32 v203, s43, v202
	s_lshl_b32 s58, s28, 12
	s_add_i32 s59, s58, s43
	s_mov_b32 s60, s59
	s_mov_b32 s61, 0
	s_lshl_b64 s[60:61], s[60:61], 14
	s_lshl_b32 s42, s27, 8
	s_add_u32 s46, s6, s60
	s_addc_u32 s47, s7, s61
	s_add_u32 s46, s46, s42
	s_addc_u32 s47, s47, 0
	s_add_u32 s52, s46, 0x3000
	s_addc_u32 s53, s47, 0
	s_mov_b32 s60, s58
	s_mov_b32 s61, 0
	s_lshl_b64 s[60:61], s[60:61], 14
	s_add_u32 s48, s6, s60
	s_addc_u32 s49, s7, s61
	s_add_u32 s48, s48, s42
	s_addc_u32 s49, s49, 0
	s_add_u32 s50, s48, 0x2000
	s_addc_u32 s51, s49, 0
	s_add_u32 s48, s48, 0x1000
	s_addc_u32 s49, s49, 0
	s_mov_b32 s60, s59
	s_mov_b32 s61, 0
	s_lshl_b64 s[60:61], s[60:61], 12
	s_add_u32 s54, s8, s60
	s_addc_u32 s55, s9, s61
	s_add_u32 s54, s54, s42
	s_addc_u32 s55, s55, 0
	s_mov_b32 s41, 0
; template <int DQK, int KA8, int DV, bool BIAS, bool JOINT>
; DI void attn_core(LAS unsigned char* lds, const bf16_t* Qrow, const bf16_t* KpA, int ldkA, const bf16_t* KpB, int ldkB, const bf16_t* Vp, int ldv,
;                   int qb, int wid, int lane, const float* qng  , f32x16 (&O)[DV / 32]) {
;     ...
;     float m = 0.f, l = 0.f; bool mnz = false;
; #pragma unroll
;     for (int dt = 0; dt < DV / 32; ++dt)
; #pragma unroll
;         for (int i = 0; i < 16; ++i) O[dt][i] = 0.f;
;     u32x4 stg[NL];
;     LAS const float* btab = (LAS const float*)(lds + 2 * STG);
;     const unsigned koff = l32 * KROW + 16 * hh, vtr = (4 * hh + tq) * VROW + (16 * blk + 4 * tp) * 2;
;     auto gload = [&](int kt) {
; #pragma unroll
;         for (int i = 0; i < NL; ++i) { const int c = tid + i * 512;
;             if (i * 512 < NKC) { const int row = c / KC, cc = c % KC;
;                 const bf16_t* src = (cc < KA8) ? KpA + (size_t)(kt * 64 + row) * ldkA + cc * 8 : KpB + (size_t)(kt * 64 + row) * ldkB + (cc - KA8) * 8;
;                 stg[i] = *(const u32x4*)src; }
;             else { const int c2 = c - NKC, row = c2 / VC, cc = c2 % VC; stg[i] = *(const u32x4*)(Vp + (size_t)(kt * 64 + row) * ldv + cc * 8); } }
;     };
;     auto lstore = [&](int buf) {
; #pragma unroll
;         for (int i = 0; i < NL; ++i) { const int c = tid + i * 512;
;             if (i * 512 < NKC) { const int row = c / KC, cc = c % KC; *(LAS u32x4*)(lds + buf * STG + row * KROW + cc * 16) = stg[i]; }
;             else { const int c2 = c - NKC, row = c2 / VC, cc = c2 % VC; *(LAS u32x4*)(lds + buf * STG + 64 * KROW + row * VROW + cc * 16) = stg[i]; } }
;     };
;     gload(0); lstore(0); __syncthreads();
;     for (int kt = 0; kt < nkt; ++kt) {
;         if (kt + 1 < nkt) gload(kt + 1);
;         if (JOINT && kt <= myc) {
;             LAS unsigned char* kb = lds + (kt & 1) * STG; LAS unsigned char* vb = kb + 64 * KROW;
;             const bool far = (kt * 64 + 63 - q0w <= -91);
;             f32x16 S0, S1;
; #pragma unroll
;             for (int i = 0; i < 16; ++i) { S0[i] = 0.f; S1[i] = 0.f; }
; #pragma unroll
;             for (int s = 0; s < DQK / 16; ++s) {
;                 const bf16x8 k0 = *(LAS const bf16x8*)(kb + koff + 32 * s), k1 = *(LAS const bf16x8*)(kb + koff + 32 * KROW + 32 * s);
;                 S0 = mfma32(k0, qf[s], S0); S1 = mfma32(k1, qf[s], S1);
;             }
.Laa_pass:
	s_barrier
	s_lshl_b32 s58, s41, 7
	s_add_u32 s30, s48, s58
	s_addc_u32 s31, s49, 0
	s_add_u32 s56, s46, s58
	s_addc_u32 s57, s47, 0
	global_load_dwordx4 v[128:131], v176, s[30:31]
	global_load_dwordx4 v[112:115], v197, s[56:57] offset:0
	global_load_dwordx4 v[116:119], v197, s[56:57] offset:32
	global_load_dwordx4 v[120:123], v197, s[56:57] offset:64
	global_load_dwordx4 v[124:127], v197, s[56:57] offset:96
	s_add_u32 s30, s30, 0x100000
	s_addc_u32 s31, s31, 0
	s_mov_b64 s[34:35], s[50:51]
	v_mov_b32_e32 v0, 0
	v_mov_b32_e32 v1, 0
	v_mov_b32_e32 v2, 0
	v_mov_b32_e32 v3, 0
	v_mov_b32_e32 v4, 0
	v_mov_b32_e32 v5, 0
	v_mov_b32_e32 v6, 0
	v_mov_b32_e32 v7, 0
	v_mov_b32_e32 v8, 0
	v_mov_b32_e32 v9, 0
	v_mov_b32_e32 v10, 0
	v_mov_b32_e32 v11, 0
	v_mov_b32_e32 v12, 0
	v_mov_b32_e32 v13, 0
	v_mov_b32_e32 v14, 0
	v_mov_b32_e32 v15, 0
	v_mov_b32_e32 v16, 0
	v_mov_b32_e32 v17, 0
	v_mov_b32_e32 v18, 0
	v_mov_b32_e32 v19, 0
	v_mov_b32_e32 v20, 0
	v_mov_b32_e32 v21, 0
	v_mov_b32_e32 v22, 0
	v_mov_b32_e32 v23, 0
	v_mov_b32_e32 v24, 0
	v_mov_b32_e32 v25, 0
	v_mov_b32_e32 v26, 0
	v_mov_b32_e32 v27, 0
	v_mov_b32_e32 v28, 0
	v_mov_b32_e32 v29, 0
	v_mov_b32_e32 v30, 0
	v_mov_b32_e32 v31, 0
	v_mov_b32_e32 v32, 0
	v_mov_b32_e32 v33, 0
	v_mov_b32_e32 v34, 0
	v_mov_b32_e32 v35, 0
	v_mov_b32_e32 v36, 0
	v_mov_b32_e32 v37, 0
	v_mov_b32_e32 v38, 0
	v_mov_b32_e32 v39, 0
	v_mov_b32_e32 v40, 0
	v_mov_b32_e32 v41, 0
	v_mov_b32_e32 v42, 0
	v_mov_b32_e32 v43, 0
	v_mov_b32_e32 v44, 0
	v_mov_b32_e32 v45, 0
	v_mov_b32_e32 v46, 0
	v_mov_b32_e32 v47, 0
	v_mov_b32_e32 v48, 0
	v_mov_b32_e32 v49, 0
	v_mov_b32_e32 v50, 0
	v_mov_b32_e32 v51, 0
	v_mov_b32_e32 v52, 0
	v_mov_b32_e32 v53, 0
	v_mov_b32_e32 v54, 0
	v_mov_b32_e32 v55, 0
	v_mov_b32_e32 v56, 0
	v_mov_b32_e32 v57, 0
	v_mov_b32_e32 v58, 0
	v_mov_b32_e32 v59, 0
	v_mov_b32_e32 v60, 0
	v_mov_b32_e32 v61, 0
	v_mov_b32_e32 v62, 0
	v_mov_b32_e32 v63, 0
	v_mov_b32_e32 v183, 0
	v_mov_b32_e32 v184, 0
	s_mov_b32 s40, 0
	s_waitcnt vmcnt(4)
	ds_write_b128 v174, v[128:131]
	s_waitcnt lgkmcnt(0)
	global_load_dwordx4 v[128:131], v176, s[30:31]
	global_load_dwordx4 v[132:135], v177, s[34:35]
	global_load_dwordx4 v[136:139], v182, s[34:35]
	s_add_u32 s30, s30, 0x100000
	s_addc_u32 s31, s31, 0
	s_add_u32 s34, s34, 0x100000
	s_addc_u32 s35, s35, 0
	s_barrier
	s_cmp_lt_u32 s26, 4
	s_cbranch_scc1 .Laa_nostag
	s_barrier
.Laa_nostag:
	s_mov_b32 s24, 0
	s_mov_b32 s36, 0
	s_mov_b32 s37, 9216
	s_mov_b32 s38, 18432
	s_mov_b32 s39, 38912
.Laa_loop:
	s_waitcnt vmcnt(0)
	s_add_i32 s58, s24, 1
	s_cmp_lt_u32 s58, s17
	s_cbranch_scc0 .Laa_xnok
	v_add_u32_e32 v186, s37, v174
	ds_write_b128 v186, v[128:131]
.Laa_xnok:
	v_add_u32_e32 v186, s38, v175
	ds_write_b128 v186, v[132:135]
	ds_write_b128 v186, v[136:139] offset:10240
	v_add_u32_e32 v187, s39, v173
	v_add_u32_e32 v188, s36, v172
	s_add_i32 s58, s25, 1
	s_cmp_eq_u32 s24, 0
	s_cbranch_scc1 .Laa_x_qk
	s_cmp_gt_u32 s24, s58
	s_cbranch_scc1 .Laa_x_end
	s_cmp_eq_u32 s24, s58
	s_cbranch_scc1 .Laa_x_pv
	ds_read_b64_tr_b16 v[140:141], v187 offset:0
	ds_read_b64_tr_b16 v[142:143], v187 offset:2560
	ds_read_b64_tr_b16 v[144:145], v187 offset:64
	ds_read_b64_tr_b16 v[146:147], v187 offset:2624
	ds_read_b64_tr_b16 v[148:149], v187 offset:128
	ds_read_b64_tr_b16 v[150:151], v187 offset:2688
	ds_read_b64_tr_b16 v[152:153], v187 offset:192
	ds_read_b64_tr_b16 v[154:155], v187 offset:2752
	ds_read_b64_tr_b16 v[156:157], v187 offset:5120
	ds_read_b64_tr_b16 v[158:159], v187 offset:7680
	ds_read_b64_tr_b16 v[160:161], v187 offset:5184
	ds_read_b64_tr_b16 v[162:163], v187 offset:7744
	s_waitcnt lgkmcnt(10)
	v_mfma_f32_32x32x16_bf16 v[0:15], v[140:143], v[96:99], v[0:15]
	ds_read_b64_tr_b16 v[164:165], v187 offset:5248
	ds_read_b64_tr_b16 v[166:167], v187 offset:7808
	s_waitcnt lgkmcnt(10)
	v_mfma_f32_32x32x16_bf16 v[16:31], v[144:147], v[96:99], v[16:31]
	ds_read_b64_tr_b16 v[168:169], v187 offset:5312
	ds_read_b64_tr_b16 v[170:171], v187 offset:7872
	s_waitcnt lgkmcnt(10)
	v_mfma_f32_32x32x16_bf16 v[32:47], v[148:151], v[96:99], v[32:47]
	ds_read_b64_tr_b16 v[140:141], v187 offset:10240
	ds_read_b64_tr_b16 v[142:143], v187 offset:12800
	s_waitcnt lgkmcnt(10)
	v_mfma_f32_32x32x16_bf16 v[48:63], v[152:155], v[96:99], v[48:63]
	ds_read_b64_tr_b16 v[144:145], v187 offset:10304
	ds_read_b64_tr_b16 v[146:147], v187 offset:12864
	s_waitcnt lgkmcnt(10)
	v_mfma_f32_32x32x16_bf16 v[0:15], v[156:159], v[100:103], v[0:15]
	ds_read_b64_tr_b16 v[148:149], v187 offset:10368
	ds_read_b64_tr_b16 v[150:151], v187 offset:12928
	s_waitcnt lgkmcnt(10)
	v_mfma_f32_32x32x16_bf16 v[16:31], v[160:163], v[100:103], v[16:31]
	ds_read_b64_tr_b16 v[152:153], v187 offset:10432
	ds_read_b64_tr_b16 v[154:155], v187 offset:12992
	s_waitcnt lgkmcnt(10)
	v_mfma_f32_32x32x16_bf16 v[32:47], v[164:167], v[100:103], v[32:47]
	ds_read_b64_tr_b16 v[156:157], v187 offset:15360
	ds_read_b64_tr_b16 v[158:159], v187 offset:17920
	s_waitcnt lgkmcnt(10)
	v_mfma_f32_32x32x16_bf16 v[48:63], v[168:171], v[100:103], v[48:63]
	ds_read_b64_tr_b16 v[160:161], v187 offset:15424
	ds_read_b64_tr_b16 v[162:163], v187 offset:17984
	s_waitcnt lgkmcnt(10)
	v_mfma_f32_32x32x16_bf16 v[0:15], v[140:143], v[104:107], v[0:15]
	ds_read_b64_tr_b16 v[164:165], v187 offset:15488
	ds_read_b64_tr_b16 v[166:167], v187 offset:18048
	s_waitcnt lgkmcnt(10)
	v_mfma_f32_32x32x16_bf16 v[16:31], v[144:147], v[104:107], v[16:31]
	ds_read_b64_tr_b16 v[168:169], v187 offset:15552
	ds_read_b64_tr_b16 v[170:171], v187 offset:18112
	s_waitcnt lgkmcnt(10)
	v_mfma_f32_32x32x16_bf16 v[32:47], v[148:151], v[104:107], v[32:47]
	ds_read_b128 v[140:143], v188 offset:0
	s_waitcnt lgkmcnt(9)
; template <int DQK, int KA8, int DV, bool BIAS, bool JOINT>
; DI void attn_core(LAS unsigned char* lds, const bf16_t* Qrow, const bf16_t* KpA, int ldkA, const bf16_t* KpB, int ldkB, const bf16_t* Vp, int ldv,
;                   int qb, int wid, int lane, const float* qng  , f32x16 (&O)[DV / 32]) {
;     ...
;             f32x16 S0, S1;
; #pragma unroll
;             for (int i = 0; i < 16; ++i) { S0[i] = 0.f; S1[i] = 0.f; }
; #pragma unroll
;             for (int s = 0; s < DQK / 16; ++s) {
;                 const bf16x8 k0 = *(LAS const bf16x8*)(kb + koff + 32 * s), k1 = *(LAS const bf16x8*)(kb + koff + 32 * KROW + 32 * s);
;                 S0 = mfma32(k0, qf[s], S0); S1 = mfma32(k1, qf[s], S1);
;             }
;             if (BIAS && !far) {
;                 const int rb = kt * 64 - (q0w + l32) + 128;
; #pragma unroll
;                 for (int i = 0; i < 16; ++i) { const int i0 = rb + crow(i, hh); S0[i] += btab[i0 < 0 ? 0 : i0]; S1[i] += btab[i0 + 32 < 0 ? 0 : i0 + 32]; }
;             }
;             if (mnz) {
; #pragma unroll
;                 for (int i = 0; i < 16; ++i) { S0[i] -= m; S1[i] -= m; }
;             }
;             float mx = fmaxf(S0[0], S1[0]);
; #pragma unroll
;             for (int i = 1; i < 16; ++i) mx = fmaxf(mx, fmaxf(S0[i], S1[i]));
;             mx = fmaxf(mx, __shfl_xor(mx, 32));
;             if (__any(mx > 64.f || (kt == 0 && mx < -64.f))) {
;                 const float dm = (mx > 64.f || (kt == 0 && mx < -64.f)) ? mx : 0.f, alpha = __builtin_amdgcn_exp2f(-dm); m += dm; mnz = true;
;                 l *= alpha;
; #pragma unroll
;                 for (int dt = 0; dt < DV / 32; ++dt) O[dt] *= alpha;
; #pragma unroll
;                 for (int i = 0; i < 16; ++i) { S0[i] -= dm; S1[i] -= dm; }
;             }
;             float ps = 0.f;
; #pragma unroll
;             for (int i = 0; i < 16; ++i) { S0[i] = __builtin_amdgcn_exp2f(S0[i]); S1[i] = __builtin_amdgcn_exp2f(S1[i]); ps += S0[i] + S1[i]; }
;             l += ps;
; #pragma unroll
;             for (int half = 0; half < 2; ++half)
; #pragma unroll
;                 for (int s = 0; s < 2; ++s) {
;                     const f32x16& S = half ? S1 : S0;
;                     u32x4 pw; pw.x = pk2(S[8 * s], S[8 * s + 1]); pw.y = pk2(S[8 * s + 2], S[8 * s + 3]); pw.z = pk2(S[8 * s + 4], S[8 * s + 5]); pw.w = pk2(S[8 * s + 6], S[8 * s + 7]);
	v_mfma_f32_32x32x16_bf16 v[48:63], v[152:155], v[104:107], v[48:63]
	ds_read_b128 v[144:147], v188 offset:4608
	s_waitcnt lgkmcnt(8)
	v_mfma_f32_32x32x16_bf16 v[0:15], v[156:159], v[108:111], v[0:15]
	ds_read_b128 v[148:151], v188 offset:32
	s_waitcnt lgkmcnt(7)
	v_mfma_f32_32x32x16_bf16 v[16:31], v[160:163], v[108:111], v[16:31]
	ds_read_b128 v[152:155], v188 offset:4640
	s_waitcnt lgkmcnt(6)
	v_mfma_f32_32x32x16_bf16 v[32:47], v[164:167], v[108:111], v[32:47]
	ds_read_b128 v[156:159], v188 offset:64
	s_waitcnt lgkmcnt(5)
	v_mfma_f32_32x32x16_bf16 v[48:63], v[168:171], v[108:111], v[48:63]
	ds_read_b128 v[160:163], v188 offset:4672
	s_waitcnt lgkmcnt(5)
	v_mfma_f32_32x32x16_bf16 v[64:79], v[140:143], v[112:115], 0
	ds_read_b128 v[164:167], v188 offset:96
	s_waitcnt lgkmcnt(5)
	v_mfma_f32_32x32x16_bf16 v[80:95], v[144:147], v[112:115], 0
	ds_read_b128 v[168:171], v188 offset:4704
	s_waitcnt lgkmcnt(5)
	v_mfma_f32_32x32x16_bf16 v[64:79], v[148:151], v[116:119], v[64:79]
	s_waitcnt lgkmcnt(4)
	v_mfma_f32_32x32x16_bf16 v[80:95], v[152:155], v[116:119], v[80:95]
	s_waitcnt lgkmcnt(3)
	v_mfma_f32_32x32x16_bf16 v[64:79], v[156:159], v[120:123], v[64:79]
	s_waitcnt lgkmcnt(2)
	v_mfma_f32_32x32x16_bf16 v[80:95], v[160:163], v[120:123], v[80:95]
	s_waitcnt lgkmcnt(1)
	v_mfma_f32_32x32x16_bf16 v[64:79], v[164:167], v[124:127], v[64:79]
	s_waitcnt lgkmcnt(0)
	v_mfma_f32_32x32x16_bf16 v[80:95], v[168:171], v[124:127], v[80:95]
	s_branch .Laa_x_end
.Laa_x_pv:
	ds_read_b64_tr_b16 v[140:141], v187 offset:0
	ds_read_b64_tr_b16 v[142:143], v187 offset:2560
	ds_read_b64_tr_b16 v[144:145], v187 offset:64
	ds_read_b64_tr_b16 v[146:147], v187 offset:2624
	ds_read_b64_tr_b16 v[148:149], v187 offset:128
	ds_read_b64_tr_b16 v[150:151], v187 offset:2688
	ds_read_b64_tr_b16 v[152:153], v187 offset:192
	ds_read_b64_tr_b16 v[154:155], v187 offset:2752
	ds_read_b64_tr_b16 v[156:157], v187 offset:5120
	ds_read_b64_tr_b16 v[158:159], v187 offset:7680
	ds_read_b64_tr_b16 v[160:161], v187 offset:5184
	ds_read_b64_tr_b16 v[162:163], v187 offset:7744
	s_waitcnt lgkmcnt(10)
	v_mfma_f32_32x32x16_bf16 v[0:15], v[140:143], v[96:99], v[0:15]
	ds_read_b64_tr_b16 v[164:165], v187 offset:5248
	ds_read_b64_tr_b16 v[166:167], v187 offset:7808
	s_waitcnt lgkmcnt(10)
	v_mfma_f32_32x32x16_bf16 v[16:31], v[144:147], v[96:99], v[16:31]
	ds_read_b64_tr_b16 v[168:169], v187 offset:5312
	ds_read_b64_tr_b16 v[170:171], v187 offset:7872
	s_waitcnt lgkmcnt(10)
	v_mfma_f32_32x32x16_bf16 v[32:47], v[148:151], v[96:99], v[32:47]
	ds_read_b64_tr_b16 v[140:141], v187 offset:10240
	ds_read_b64_tr_b16 v[142:143], v187 offset:12800
	s_waitcnt lgkmcnt(10)
	v_mfma_f32_32x32x16_bf16 v[48:63], v[152:155], v[96:99], v[48:63]
	ds_read_b64_tr_b16 v[144:145], v187 offset:10304
	ds_read_b64_tr_b16 v[146:147], v187 offset:12864
	s_waitcnt lgkmcnt(10)
	v_mfma_f32_32x32x16_bf16 v[0:15], v[156:159], v[100:103], v[0:15]
	ds_read_b64_tr_b16 v[148:149], v187 offset:10368
	ds_read_b64_tr_b16 v[150:151], v187 offset:12928
	s_waitcnt lgkmcnt(10)
	v_mfma_f32_32x32x16_bf16 v[16:31], v[160:163], v[100:103], v[16:31]
	ds_read_b64_tr_b16 v[152:153], v187 offset:10432
	ds_read_b64_tr_b16 v[154:155], v187 offset:12992
	s_waitcnt lgkmcnt(10)
	v_mfma_f32_32x32x16_bf16 v[32:47], v[164:167], v[100:103], v[32:47]
	ds_read_b64_tr_b16 v[156:157], v187 offset:15360
	ds_read_b64_tr_b16 v[158:159], v187 offset:17920
	s_waitcnt lgkmcnt(10)
	v_mfma_f32_32x32x16_bf16 v[48:63], v[168:171], v[100:103], v[48:63]
	ds_read_b64_tr_b16 v[160:161], v187 offset:15424
	ds_read_b64_tr_b16 v[162:163], v187 offset:17984
	s_waitcnt lgkmcnt(10)
	v_mfma_f32_32x32x16_bf16 v[0:15], v[140:143], v[104:107], v[0:15]
	ds_read_b64_tr_b16 v[164:165], v187 offset:15488
	ds_read_b64_tr_b16 v[166:167], v187 offset:18048
	s_waitcnt lgkmcnt(10)
	v_mfma_f32_32x32x16_bf16 v[16:31], v[144:147], v[104:107], v[16:31]
	ds_read_b64_tr_b16 v[168:169], v187 offset:15552
	ds_read_b64_tr_b16 v[170:171], v187 offset:18112
	s_waitcnt lgkmcnt(10)
	v_mfma_f32_32x32x16_bf16 v[32:47], v[148:151], v[104:107], v[32:47]
	s_waitcnt lgkmcnt(8)
	v_mfma_f32_32x32x16_bf16 v[48:63], v[152:155], v[104:107], v[48:63]
	s_waitcnt lgkmcnt(6)
	v_mfma_f32_32x32x16_bf16 v[0:15], v[156:159], v[108:111], v[0:15]
	s_waitcnt lgkmcnt(4)
	v_mfma_f32_32x32x16_bf16 v[16:31], v[160:163], v[108:111], v[16:31]
	s_waitcnt lgkmcnt(2)
	v_mfma_f32_32x32x16_bf16 v[32:47], v[164:167], v[108:111], v[32:47]
	s_waitcnt lgkmcnt(0)
	v_mfma_f32_32x32x16_bf16 v[48:63], v[168:171], v[108:111], v[48:63]
	s_branch .Laa_x_end
.Laa_x_qk:
	ds_read_b128 v[140:143], v188 offset:0
	ds_read_b128 v[144:147], v188 offset:4608
	ds_read_b128 v[148:151], v188 offset:32
	ds_read_b128 v[152:155], v188 offset:4640
	ds_read_b128 v[156:159], v188 offset:64
	ds_read_b128 v[160:163], v188 offset:4672
	s_waitcnt lgkmcnt(5)
	v_mfma_f32_32x32x16_bf16 v[64:79], v[140:143], v[112:115], 0
	ds_read_b128 v[164:167], v188 offset:96
	s_waitcnt lgkmcnt(5)
	v_mfma_f32_32x32x16_bf16 v[80:95], v[144:147], v[112:115], 0
	ds_read_b128 v[168:171], v188 offset:4704
	s_waitcnt lgkmcnt(5)
	v_mfma_f32_32x32x16_bf16 v[64:79], v[148:151], v[116:119], v[64:79]
	s_waitcnt lgkmcnt(4)
	v_mfma_f32_32x32x16_bf16 v[80:95], v[152:155], v[116:119], v[80:95]
	s_waitcnt lgkmcnt(3)
	v_mfma_f32_32x32x16_bf16 v[64:79], v[156:159], v[120:123], v[64:79]
	s_waitcnt lgkmcnt(2)
	v_mfma_f32_32x32x16_bf16 v[80:95], v[160:163], v[120:123], v[80:95]
	s_waitcnt lgkmcnt(1)
	v_mfma_f32_32x32x16_bf16 v[64:79], v[164:167], v[124:127], v[64:79]
	s_waitcnt lgkmcnt(0)
	v_mfma_f32_32x32x16_bf16 v[80:95], v[168:171], v[124:127], v[80:95]
; #define LAS __attribute__((address_space(3)))
; DI int crow(int i, int hh) { return (i & 3) + 8 * (i >> 2) + 4 * hh; }
; DI f32x16 mfma32(bf16x8 a, bf16x8 b, f32x16 c) { return __builtin_amdgcn_mfma_f32_32x32x16_bf16(a, b, c, 0, 0, 0); }
; template <int DQK, int KA8, int DV, bool BIAS, bool JOINT>
; DI void attn_core(LAS unsigned char* lds, const bf16_t* Qrow, const bf16_t* KpA, int ldkA, const bf16_t* KpB, int ldkB, const bf16_t* Vp, int ldv,
;                   int qb, int wid, int lane, const float* qng  , f32x16 (&O)[DV / 32]) {
;     ...
;         if (kt + 1 < nkt) gload(kt + 1);
;         if (JOINT && kt <= myc) {
;             LAS unsigned char* kb = lds + (kt & 1) * STG; LAS unsigned char* vb = kb + 64 * KROW;
;             const bool far = (kt * 64 + 63 - q0w <= -91);
;             f32x16 S0, S1;
; #pragma unroll
;             for (int i = 0; i < 16; ++i) { S0[i] = 0.f; S1[i] = 0.f; }
; #pragma unroll
;             for (int s = 0; s < DQK / 16; ++s) {
;                 const bf16x8 k0 = *(LAS const bf16x8*)(kb + koff + 32 * s), k1 = *(LAS const bf16x8*)(kb + koff + 32 * KROW + 32 * s);
;                 S0 = mfma32(k0, qf[s], S0); S1 = mfma32(k1, qf[s], S1);
;             }
;             if (BIAS && !far) {
;                 const int rb = kt * 64 - (q0w + l32) + 128;
; #pragma unroll
;                 for (int i = 0; i < 16; ++i) { const int i0 = rb + crow(i, hh); S0[i] += btab[i0 < 0 ? 0 : i0]; S1[i] += btab[i0 + 32 < 0 ? 0 : i0 + 32]; }
; DI void phase_attn_a(const Params& p, LAS unsigned char* lds) {
;     ...
;     for (int i = 0; i < 64; ++i) { d0 += p.in[5][i] * p.in[5][64 + i]; d1 += p.in[5][128 + i] * p.in[5][192 + i]; }
.Laa_x_end:
	s_waitcnt lgkmcnt(0)
	s_barrier
	s_add_i32 s58, s24, 2
	s_cmp_lt_u32 s58, s17
	s_cbranch_scc0 .Laa_ynok
	global_load_dwordx4 v[128:131], v176, s[30:31]
	s_add_u32 s30, s30, 0x100000
	s_addc_u32 s31, s31, 0
.Laa_ynok:
	s_add_i32 s58, s24, 1
	s_cmp_lt_u32 s58, s17
	s_cbranch_scc0 .Laa_ynov
	global_load_dwordx4 v[132:135], v177, s[34:35]
	global_load_dwordx4 v[136:139], v182, s[34:35]
	s_add_u32 s34, s34, 0x100000
	s_addc_u32 s35, s35, 0
.Laa_ynov:
	s_cmp_gt_u32 s24, s25
	s_cbranch_scc1 .Laa_y_end
	s_nop 15
	s_lshl_b32 s58, s24, 6
	s_add_i32 s59, s58, 154
	s_cmp_gt_i32 s59, s43
	s_cbranch_scc0 .Laa_nobias
	v_add_u32_e32 v186, s58, v203
	v_max_i32_e32 v188, 0xffffffe0, v186
	v_max_i32_e32 v187, 0, v186
	v_lshlrev_b32_e32 v187, 2, v187
	v_lshlrev_b32_e32 v188, 2, v188
	ds_read_b32 v140, v187 offset:59392
	ds_read_b32 v156, v188 offset:59520
	v_add_u32_e32 v189, 1, v186
	v_max_i32_e32 v190, 0xffffffe0, v189
	v_max_i32_e32 v189, 0, v189
	v_lshlrev_b32_e32 v189, 2, v189
	v_lshlrev_b32_e32 v190, 2, v190
	ds_read_b32 v141, v189 offset:59392
	ds_read_b32 v157, v190 offset:59520
	v_add_u32_e32 v193, 2, v186
	v_max_i32_e32 v195, 0xffffffe0, v193
	v_max_i32_e32 v193, 0, v193
	v_lshlrev_b32_e32 v193, 2, v193
	v_lshlrev_b32_e32 v195, 2, v195
	ds_read_b32 v142, v193 offset:59392
	ds_read_b32 v158, v195 offset:59520
	v_add_u32_e32 v196, 3, v186
	v_max_i32_e32 v204, 0xffffffe0, v196
	v_max_i32_e32 v196, 0, v196
	v_lshlrev_b32_e32 v196, 2, v196
	v_lshlrev_b32_e32 v204, 2, v204
	ds_read_b32 v143, v196 offset:59392
	ds_read_b32 v159, v204 offset:59520
	s_waitcnt lgkmcnt(0)
	v_add_f32_e32 v64, v64, v140
	v_add_f32_e32 v80, v80, v156
	v_add_f32_e32 v65, v65, v141
	v_add_f32_e32 v81, v81, v157
	v_add_f32_e32 v66, v66, v142
	v_add_f32_e32 v82, v82, v158
	v_add_f32_e32 v67, v67, v143
	v_add_f32_e32 v83, v83, v159
	v_add_u32_e32 v187, 8, v186
	v_max_i32_e32 v188, 0xffffffe0, v187
	v_max_i32_e32 v187, 0, v187
	v_lshlrev_b32_e32 v187, 2, v187
	v_lshlrev_b32_e32 v188, 2, v188
	ds_read_b32 v144, v187 offset:59392
	ds_read_b32 v160, v188 offset:59520
	v_add_u32_e32 v189, 9, v186
	v_max_i32_e32 v190, 0xffffffe0, v189
	v_max_i32_e32 v189, 0, v189
	v_lshlrev_b32_e32 v189, 2, v189
	v_lshlrev_b32_e32 v190, 2, v190
	ds_read_b32 v145, v189 offset:59392
	ds_read_b32 v161, v190 offset:59520
	v_add_u32_e32 v193, 10, v186
	v_max_i32_e32 v195, 0xffffffe0, v193
	v_max_i32_e32 v193, 0, v193
	v_lshlrev_b32_e32 v193, 2, v193
	v_lshlrev_b32_e32 v195, 2, v195
	ds_read_b32 v146, v193 offset:59392
	ds_read_b32 v162, v195 offset:59520
	v_add_u32_e32 v196, 11, v186
	v_max_i32_e32 v204, 0xffffffe0, v196
	v_max_i32_e32 v196, 0, v196
	v_lshlrev_b32_e32 v196, 2, v196
	v_lshlrev_b32_e32 v204, 2, v204
	ds_read_b32 v147, v196 offset:59392
	ds_read_b32 v163, v204 offset:59520
	s_waitcnt lgkmcnt(0)
	v_add_f32_e32 v68, v68, v144
	v_add_f32_e32 v84, v84, v160
	v_add_f32_e32 v69, v69, v145
	v_add_f32_e32 v85, v85, v161
	v_add_f32_e32 v70, v70, v146
	v_add_f32_e32 v86, v86, v162
	v_add_f32_e32 v71, v71, v147
	v_add_f32_e32 v87, v87, v163
	v_add_u32_e32 v187, 16, v186
	v_max_i32_e32 v188, 0xffffffe0, v187
	v_max_i32_e32 v187, 0, v187
	v_lshlrev_b32_e32 v187, 2, v187
	v_lshlrev_b32_e32 v188, 2, v188
	ds_read_b32 v148, v187 offset:59392
	ds_read_b32 v164, v188 offset:59520
	v_add_u32_e32 v189, 17, v186
	v_max_i32_e32 v190, 0xffffffe0, v189
	v_max_i32_e32 v189, 0, v189
	v_lshlrev_b32_e32 v189, 2, v189
	v_lshlrev_b32_e32 v190, 2, v190
	ds_read_b32 v149, v189 offset:59392
	ds_read_b32 v165, v190 offset:59520
	v_add_u32_e32 v193, 18, v186
	v_max_i32_e32 v195, 0xffffffe0, v193
	v_max_i32_e32 v193, 0, v193
	v_lshlrev_b32_e32 v193, 2, v193
	v_lshlrev_b32_e32 v195, 2, v195
	ds_read_b32 v150, v193 offset:59392
	ds_read_b32 v166, v195 offset:59520
	v_add_u32_e32 v196, 19, v186
	v_max_i32_e32 v204, 0xffffffe0, v196
	v_max_i32_e32 v196, 0, v196
	v_lshlrev_b32_e32 v196, 2, v196
	v_lshlrev_b32_e32 v204, 2, v204
	ds_read_b32 v151, v196 offset:59392
	ds_read_b32 v167, v204 offset:59520
	s_waitcnt lgkmcnt(0)
	v_add_f32_e32 v72, v72, v148
	v_add_f32_e32 v88, v88, v164
	v_add_f32_e32 v73, v73, v149
	v_add_f32_e32 v89, v89, v165
	v_add_f32_e32 v74, v74, v150
	v_add_f32_e32 v90, v90, v166
	v_add_f32_e32 v75, v75, v151
	v_add_f32_e32 v91, v91, v167
	v_add_u32_e32 v187, 24, v186
	v_max_i32_e32 v188, 0xffffffe0, v187
	v_max_i32_e32 v187, 0, v187
	v_lshlrev_b32_e32 v187, 2, v187
	v_lshlrev_b32_e32 v188, 2, v188
	ds_read_b32 v152, v187 offset:59392
	ds_read_b32 v168, v188 offset:59520
	v_add_u32_e32 v189, 25, v186
	v_max_i32_e32 v190, 0xffffffe0, v189
	v_max_i32_e32 v189, 0, v189
	v_lshlrev_b32_e32 v189, 2, v189
	v_lshlrev_b32_e32 v190, 2, v190
	ds_read_b32 v153, v189 offset:59392
	ds_read_b32 v169, v190 offset:59520
	v_add_u32_e32 v193, 26, v186
	v_max_i32_e32 v195, 0xffffffe0, v193
	v_max_i32_e32 v193, 0, v193
	v_lshlrev_b32_e32 v193, 2, v193
	v_lshlrev_b32_e32 v195, 2, v195
	ds_read_b32 v154, v193 offset:59392
	ds_read_b32 v170, v195 offset:59520
	v_add_u32_e32 v196, 27, v186
	v_max_i32_e32 v204, 0xffffffe0, v196
	v_max_i32_e32 v196, 0, v196
	v_lshlrev_b32_e32 v196, 2, v196
	v_lshlrev_b32_e32 v204, 2, v204
	ds_read_b32 v155, v196 offset:59392
	ds_read_b32 v171, v204 offset:59520
	s_waitcnt lgkmcnt(0)
	v_add_f32_e32 v76, v76, v152
	v_add_f32_e32 v92, v92, v168
	v_add_f32_e32 v77, v77, v153
	v_add_f32_e32 v93, v93, v169
	v_add_f32_e32 v78, v78, v154
	v_add_f32_e32 v94, v94, v170
	v_add_f32_e32 v79, v79, v155
	v_add_f32_e32 v95, v95, v171
; template <int DQK, int KA8, int DV, bool BIAS, bool JOINT>
; DI void attn_core(LAS unsigned char* lds, const bf16_t* Qrow, const bf16_t* KpA, int ldkA, const bf16_t* KpB, int ldkB, const bf16_t* Vp, int ldv,
;                   int qb, int wid, int lane, const float* qng  , f32x16 (&O)[DV / 32]) {
;     ...
;             if (mnz) {
; #pragma unroll
;                 for (int i = 0; i < 16; ++i) { S0[i] -= m; S1[i] -= m; }
;             }
;             float mx = fmaxf(S0[0], S1[0]);
; #pragma unroll
;             for (int i = 1; i < 16; ++i) mx = fmaxf(mx, fmaxf(S0[i], S1[i]));
;             mx = fmaxf(mx, __shfl_xor(mx, 32));
;             if (__any(mx > 64.f || (kt == 0 && mx < -64.f))) {
;                 const float dm = (mx > 64.f || (kt == 0 && mx < -64.f)) ? mx : 0.f, alpha = __builtin_amdgcn_exp2f(-dm); m += dm; mnz = true;
;                 l *= alpha;
; #pragma unroll
;                 for (int dt = 0; dt < DV / 32; ++dt) O[dt] *= alpha;
; #pragma unroll
;                 for (int i = 0; i < 16; ++i) { S0[i] -= dm; S1[i] -= dm; }
;             }
.Laa_nobias:
	s_cmp_eq_u32 s40, 0
	s_cbranch_scc1 .Laa_nosubm
	v_sub_f32_e32 v64, v64, v183
	v_sub_f32_e32 v65, v65, v183
	v_sub_f32_e32 v66, v66, v183
	v_sub_f32_e32 v67, v67, v183
	v_sub_f32_e32 v68, v68, v183
	v_sub_f32_e32 v69, v69, v183
	v_sub_f32_e32 v70, v70, v183
	v_sub_f32_e32 v71, v71, v183
	v_sub_f32_e32 v72, v72, v183
	v_sub_f32_e32 v73, v73, v183
	v_sub_f32_e32 v74, v74, v183
	v_sub_f32_e32 v75, v75, v183
	v_sub_f32_e32 v76, v76, v183
	v_sub_f32_e32 v77, v77, v183
	v_sub_f32_e32 v78, v78, v183
	v_sub_f32_e32 v79, v79, v183
	v_sub_f32_e32 v80, v80, v183
	v_sub_f32_e32 v81, v81, v183
	v_sub_f32_e32 v82, v82, v183
	v_sub_f32_e32 v83, v83, v183
	v_sub_f32_e32 v84, v84, v183
	v_sub_f32_e32 v85, v85, v183
	v_sub_f32_e32 v86, v86, v183
	v_sub_f32_e32 v87, v87, v183
	v_sub_f32_e32 v88, v88, v183
	v_sub_f32_e32 v89, v89, v183
	v_sub_f32_e32 v90, v90, v183
	v_sub_f32_e32 v91, v91, v183
	v_sub_f32_e32 v92, v92, v183
	v_sub_f32_e32 v93, v93, v183
	v_sub_f32_e32 v94, v94, v183
	v_sub_f32_e32 v95, v95, v183
.Laa_nosubm:
	v_max3_f32 v186, v64, v65, v66
	v_max3_f32 v189, v67, v68, v69
	v_max3_f32 v190, v70, v71, v72
	v_max3_f32 v193, v73, v74, v75
	v_max3_f32 v186, v186, v76, v77
	v_max3_f32 v189, v189, v78, v79
	v_max3_f32 v190, v190, v80, v81
	v_max3_f32 v193, v193, v82, v83
	v_max3_f32 v186, v186, v84, v85
	v_max3_f32 v189, v189, v86, v87
	v_max3_f32 v190, v190, v88, v89
	v_max3_f32 v193, v193, v90, v91
	v_max3_f32 v186, v186, v92, v93
	v_max3_f32 v189, v189, v94, v95
	v_max3_f32 v186, v186, v189, v190
	v_max_f32_e32 v186, v186, v193
	v_mov_b32_e32 v187, v186
	v_mov_b32_e32 v188, v186
	s_nop 1
	v_permlane32_swap_b32_e32 v187, v188
	s_nop 1
	v_max_f32_e32 v186, v187, v188
	v_cmp_lt_f32_e32 vcc, 0x42800000, v186
	s_cmp_lg_u32 s24, 0
	s_cbranch_scc1 .Laa_notfirst
	v_mov_b32_e32 v189, 0xc2800000
	v_cmp_lt_f32_e64 s[44:45], v186, v189
	s_or_b64 vcc, vcc, s[44:45]
.Laa_notfirst:
	s_cmp_lg_u64 vcc, 0
	s_cbranch_scc0 .Laa_noresc
	s_nop 3
	v_cndmask_b32_e32 v189, 0, v186, vcc
	v_exp_f32_e64 v190, -v189
	v_add_f32_e32 v183, v183, v189
	s_mov_b32 s40, 1
	v_mul_f32_e32 v184, v184, v190
	v_mul_f32_e32 v0, v0, v190
	v_mul_f32_e32 v1, v1, v190
	v_mul_f32_e32 v2, v2, v190
	v_mul_f32_e32 v3, v3, v190
	v_mul_f32_e32 v4, v4, v190
	v_mul_f32_e32 v5, v5, v190
	v_mul_f32_e32 v6, v6, v190
	v_mul_f32_e32 v7, v7, v190
	v_mul_f32_e32 v8, v8, v190
	v_mul_f32_e32 v9, v9, v190
	v_mul_f32_e32 v10, v10, v190
	v_mul_f32_e32 v11, v11, v190
	v_mul_f32_e32 v12, v12, v190
	v_mul_f32_e32 v13, v13, v190
	v_mul_f32_e32 v14, v14, v190
	v_mul_f32_e32 v15, v15, v190
	v_mul_f32_e32 v16, v16, v190
	v_mul_f32_e32 v17, v17, v190
	v_mul_f32_e32 v18, v18, v190
	v_mul_f32_e32 v19, v19, v190
	v_mul_f32_e32 v20, v20, v190
	v_mul_f32_e32 v21, v21, v190
	v_mul_f32_e32 v22, v22, v190
	v_mul_f32_e32 v23, v23, v190
	v_mul_f32_e32 v24, v24, v190
	v_mul_f32_e32 v25, v25, v190
	v_mul_f32_e32 v26, v26, v190
	v_mul_f32_e32 v27, v27, v190
	v_mul_f32_e32 v28, v28, v190
	v_mul_f32_e32 v29, v29, v190
	v_mul_f32_e32 v30, v30, v190
	v_mul_f32_e32 v31, v31, v190
	v_mul_f32_e32 v32, v32, v190
	v_mul_f32_e32 v33, v33, v190
	v_mul_f32_e32 v34, v34, v190
	v_mul_f32_e32 v35, v35, v190
	v_mul_f32_e32 v36, v36, v190
	v_mul_f32_e32 v37, v37, v190
	v_mul_f32_e32 v38, v38, v190
	v_mul_f32_e32 v39, v39, v190
	v_mul_f32_e32 v40, v40, v190
	v_mul_f32_e32 v41, v41, v190
	v_mul_f32_e32 v42, v42, v190
	v_mul_f32_e32 v43, v43, v190
	v_mul_f32_e32 v44, v44, v190
	v_mul_f32_e32 v45, v45, v190
	v_mul_f32_e32 v46, v46, v190
	v_mul_f32_e32 v47, v47, v190
	v_mul_f32_e32 v48, v48, v190
	v_mul_f32_e32 v49, v49, v190
	v_mul_f32_e32 v50, v50, v190
	v_mul_f32_e32 v51, v51, v190
	v_mul_f32_e32 v52, v52, v190
	v_mul_f32_e32 v53, v53, v190
	v_mul_f32_e32 v54, v54, v190
	v_mul_f32_e32 v55, v55, v190
	v_mul_f32_e32 v56, v56, v190
	v_mul_f32_e32 v57, v57, v190
	v_mul_f32_e32 v58, v58, v190
	v_mul_f32_e32 v59, v59, v190
	v_mul_f32_e32 v60, v60, v190
	v_mul_f32_e32 v61, v61, v190
	v_mul_f32_e32 v62, v62, v190
	v_mul_f32_e32 v63, v63, v190
	v_sub_f32_e32 v64, v64, v189
	v_sub_f32_e32 v65, v65, v189
	v_sub_f32_e32 v66, v66, v189
	v_sub_f32_e32 v67, v67, v189
	v_sub_f32_e32 v68, v68, v189
	v_sub_f32_e32 v69, v69, v189
	v_sub_f32_e32 v70, v70, v189
	v_sub_f32_e32 v71, v71, v189
	v_sub_f32_e32 v72, v72, v189
	v_sub_f32_e32 v73, v73, v189
	v_sub_f32_e32 v74, v74, v189
	v_sub_f32_e32 v75, v75, v189
	v_sub_f32_e32 v76, v76, v189
	v_sub_f32_e32 v77, v77, v189
	v_sub_f32_e32 v78, v78, v189
	v_sub_f32_e32 v79, v79, v189
	v_sub_f32_e32 v80, v80, v189
	v_sub_f32_e32 v81, v81, v189
	v_sub_f32_e32 v82, v82, v189
	v_sub_f32_e32 v83, v83, v189
	v_sub_f32_e32 v84, v84, v189
	v_sub_f32_e32 v85, v85, v189
	v_sub_f32_e32 v86, v86, v189
	v_sub_f32_e32 v87, v87, v189
	v_sub_f32_e32 v88, v88, v189
	v_sub_f32_e32 v89, v89, v189
	v_sub_f32_e32 v90, v90, v189
	v_sub_f32_e32 v91, v91, v189
	v_sub_f32_e32 v92, v92, v189
	v_sub_f32_e32 v93, v93, v189
	v_sub_f32_e32 v94, v94, v189
	v_sub_f32_e32 v95, v95, v189
; #define LAS __attribute__((address_space(3)))
; DI unsigned pk2(float a, float b) { f32x2 v = {a, b}; bf16v2_t r = __builtin_convertvector(v, bf16v2_t); return __builtin_bit_cast(unsigned, r); }
; DI f32x16 mfma32(bf16x8 a, bf16x8 b, f32x16 c) { return __builtin_amdgcn_mfma_f32_32x32x16_bf16(a, b, c, 0, 0, 0); }
; DI s16x4 trread(LAS unsigned char* p) { return __builtin_amdgcn_ds_read_tr16_b64_v4i16((LAS s16x4*)p); }
; DI bf16x8 cat4(s16x4 lo, s16x4 hi) { return __builtin_shufflevector(lo, hi, 0, 1, 2, 3, 4, 5, 6, 7); }
; template <int DQK, int KA8, int DV, bool BIAS, bool JOINT>
; DI void attn_core(LAS unsigned char* lds, const bf16_t* Qrow, const bf16_t* KpA, int ldkA, const bf16_t* KpB, int ldkB, const bf16_t* Vp, int ldv,
;                   int qb, int wid, int lane, const float* qng  , f32x16 (&O)[DV / 32]) {
;     ...
;             float ps = 0.f;
; #pragma unroll
;             for (int i = 0; i < 16; ++i) { S0[i] = __builtin_amdgcn_exp2f(S0[i]); S1[i] = __builtin_amdgcn_exp2f(S1[i]); ps += S0[i] + S1[i]; }
;             l += ps;
; #pragma unroll
;             for (int half = 0; half < 2; ++half)
; #pragma unroll
;                 for (int s = 0; s < 2; ++s) {
;                     const f32x16& S = half ? S1 : S0;
;                     u32x4 pw; pw.x = pk2(S[8 * s], S[8 * s + 1]); pw.y = pk2(S[8 * s + 2], S[8 * s + 3]); pw.z = pk2(S[8 * s + 4], S[8 * s + 5]); pw.w = pk2(S[8 * s + 6], S[8 * s + 7]);
;                     const bf16x8 pf = __builtin_bit_cast(bf16x8, pw);
;                     LAS unsigned char* vr = vb + vtr + (32 * half + 16 * s) * VROW;
; #pragma unroll
;                     for (int dt = 0; dt < DV / 32; ++dt) {
;                         const bf16x8 vf = cat4(trread(vr + 64 * dt), trread(vr + 8 * VROW + 64 * dt));
;                         O[dt] = mfma32(vf, pf, O[dt]);
;                     }
;                 }
;         }
.Laa_noresc:
	v_exp_f32_e32 v64, v64
	v_exp_f32_e32 v65, v65
	v_exp_f32_e32 v66, v66
	v_exp_f32_e32 v67, v67
	v_exp_f32_e32 v68, v68
	v_exp_f32_e32 v69, v69
	v_exp_f32_e32 v70, v70
	v_exp_f32_e32 v71, v71
	v_exp_f32_e32 v72, v72
	v_exp_f32_e32 v73, v73
	v_exp_f32_e32 v74, v74
	v_exp_f32_e32 v75, v75
	v_exp_f32_e32 v76, v76
	v_exp_f32_e32 v77, v77
	v_exp_f32_e32 v78, v78
	v_exp_f32_e32 v79, v79
	v_exp_f32_e32 v80, v80
	v_exp_f32_e32 v81, v81
	v_exp_f32_e32 v82, v82
	v_exp_f32_e32 v83, v83
	v_exp_f32_e32 v84, v84
	v_exp_f32_e32 v85, v85
	v_exp_f32_e32 v86, v86
	v_exp_f32_e32 v87, v87
	v_exp_f32_e32 v88, v88
	v_exp_f32_e32 v89, v89
	v_exp_f32_e32 v90, v90
	v_exp_f32_e32 v91, v91
	v_exp_f32_e32 v92, v92
	v_exp_f32_e32 v93, v93
	v_exp_f32_e32 v94, v94
	v_exp_f32_e32 v95, v95
	v_add_f32_e32 v186, v64, v65
	v_add_f32_e32 v189, v66, v67
	v_add_f32_e32 v190, v68, v69
	v_add_f32_e32 v193, v70, v71
	v_add_f32_e32 v186, v186, v72
	v_add_f32_e32 v189, v189, v73
	v_add_f32_e32 v190, v190, v74
	v_add_f32_e32 v193, v193, v75
	v_add_f32_e32 v186, v186, v76
	v_add_f32_e32 v189, v189, v77
	v_add_f32_e32 v190, v190, v78
	v_add_f32_e32 v193, v193, v79
	v_add_f32_e32 v186, v186, v80
	v_add_f32_e32 v189, v189, v81
	v_add_f32_e32 v190, v190, v82
	v_add_f32_e32 v193, v193, v83
	v_add_f32_e32 v186, v186, v84
	v_add_f32_e32 v189, v189, v85
	v_add_f32_e32 v190, v190, v86
	v_add_f32_e32 v193, v193, v87
	v_add_f32_e32 v186, v186, v88
	v_add_f32_e32 v189, v189, v89
	v_add_f32_e32 v190, v190, v90
	v_add_f32_e32 v193, v193, v91
	v_add_f32_e32 v186, v186, v92
	v_add_f32_e32 v189, v189, v93
	v_add_f32_e32 v190, v190, v94
	v_add_f32_e32 v193, v193, v95
	v_add_f32_e32 v186, v186, v189
	v_add_f32_e32 v190, v190, v193
	v_add_f32_e32 v186, v186, v190
	v_add_f32_e32 v184, v184, v186
	v_cvt_pk_bf16_f32 v96, v64, v65
	v_cvt_pk_bf16_f32 v97, v66, v67
	v_cvt_pk_bf16_f32 v98, v68, v69
	v_cvt_pk_bf16_f32 v99, v70, v71
	v_cvt_pk_bf16_f32 v100, v72, v73
	v_cvt_pk_bf16_f32 v101, v74, v75
	v_cvt_pk_bf16_f32 v102, v76, v77
	v_cvt_pk_bf16_f32 v103, v78, v79
	v_cvt_pk_bf16_f32 v104, v80, v81
	v_cvt_pk_bf16_f32 v105, v82, v83
	v_cvt_pk_bf16_f32 v106, v84, v85
	v_cvt_pk_bf16_f32 v107, v86, v87
	v_cvt_pk_bf16_f32 v108, v88, v89
	v_cvt_pk_bf16_f32 v109, v90, v91
	v_cvt_pk_bf16_f32 v110, v92, v93
	v_cvt_pk_bf16_f32 v111, v94, v95
.Laa_y_end:
	s_barrier
	s_mov_b32 s58, s36
	s_mov_b32 s36, s37
	s_mov_b32 s37, s58
	s_mov_b32 s58, s38
	s_mov_b32 s38, s39
	s_mov_b32 s39, s58
	s_add_i32 s24, s24, 1
	s_cmp_lt_u32 s24, s17
	s_cbranch_scc1 .Laa_loop
	s_add_i32 s58, s25, 1
	s_cmp_ge_u32 s58, s17
	s_cbranch_scc0 .Laa_nofpv
	v_add_u32_e32 v187, s39, v173
	ds_read_b64_tr_b16 v[140:141], v187 offset:0
	ds_read_b64_tr_b16 v[142:143], v187 offset:2560
	ds_read_b64_tr_b16 v[144:145], v187 offset:64
	ds_read_b64_tr_b16 v[146:147], v187 offset:2624
	ds_read_b64_tr_b16 v[148:149], v187 offset:128
	ds_read_b64_tr_b16 v[150:151], v187 offset:2688
	ds_read_b64_tr_b16 v[152:153], v187 offset:192
	ds_read_b64_tr_b16 v[154:155], v187 offset:2752
	ds_read_b64_tr_b16 v[156:157], v187 offset:5120
	ds_read_b64_tr_b16 v[158:159], v187 offset:7680
	ds_read_b64_tr_b16 v[160:161], v187 offset:5184
	ds_read_b64_tr_b16 v[162:163], v187 offset:7744
	s_waitcnt lgkmcnt(10)
	v_mfma_f32_32x32x16_bf16 v[0:15], v[140:143], v[96:99], v[0:15]
	ds_read_b64_tr_b16 v[164:165], v187 offset:5248
	ds_read_b64_tr_b16 v[166:167], v187 offset:7808
	s_waitcnt lgkmcnt(10)
	v_mfma_f32_32x32x16_bf16 v[16:31], v[144:147], v[96:99], v[16:31]
	ds_read_b64_tr_b16 v[168:169], v187 offset:5312
	ds_read_b64_tr_b16 v[170:171], v187 offset:7872
	s_waitcnt lgkmcnt(10)
	v_mfma_f32_32x32x16_bf16 v[32:47], v[148:151], v[96:99], v[32:47]
	ds_read_b64_tr_b16 v[140:141], v187 offset:10240
	ds_read_b64_tr_b16 v[142:143], v187 offset:12800
	s_waitcnt lgkmcnt(10)
	v_mfma_f32_32x32x16_bf16 v[48:63], v[152:155], v[96:99], v[48:63]
	ds_read_b64_tr_b16 v[144:145], v187 offset:10304
	ds_read_b64_tr_b16 v[146:147], v187 offset:12864
	s_waitcnt lgkmcnt(10)
	v_mfma_f32_32x32x16_bf16 v[0:15], v[156:159], v[100:103], v[0:15]
	ds_read_b64_tr_b16 v[148:149], v187 offset:10368
	ds_read_b64_tr_b16 v[150:151], v187 offset:12928
	s_waitcnt lgkmcnt(10)
	v_mfma_f32_32x32x16_bf16 v[16:31], v[160:163], v[100:103], v[16:31]
	ds_read_b64_tr_b16 v[152:153], v187 offset:10432
	ds_read_b64_tr_b16 v[154:155], v187 offset:12992
	s_waitcnt lgkmcnt(10)
	v_mfma_f32_32x32x16_bf16 v[32:47], v[164:167], v[100:103], v[32:47]
	ds_read_b64_tr_b16 v[156:157], v187 offset:15360
	ds_read_b64_tr_b16 v[158:159], v187 offset:17920
	s_waitcnt lgkmcnt(10)
	v_mfma_f32_32x32x16_bf16 v[48:63], v[168:171], v[100:103], v[48:63]
	ds_read_b64_tr_b16 v[160:161], v187 offset:15424
	ds_read_b64_tr_b16 v[162:163], v187 offset:17984
	s_waitcnt lgkmcnt(10)
	v_mfma_f32_32x32x16_bf16 v[0:15], v[140:143], v[104:107], v[0:15]
	ds_read_b64_tr_b16 v[164:165], v187 offset:15488
	ds_read_b64_tr_b16 v[166:167], v187 offset:18048
	s_waitcnt lgkmcnt(10)
	v_mfma_f32_32x32x16_bf16 v[16:31], v[144:147], v[104:107], v[16:31]
	ds_read_b64_tr_b16 v[168:169], v187 offset:15552
	ds_read_b64_tr_b16 v[170:171], v187 offset:18112
	s_waitcnt lgkmcnt(10)
	v_mfma_f32_32x32x16_bf16 v[32:47], v[148:151], v[104:107], v[32:47]
	s_waitcnt lgkmcnt(8)
	v_mfma_f32_32x32x16_bf16 v[48:63], v[152:155], v[104:107], v[48:63]
	s_waitcnt lgkmcnt(6)
	v_mfma_f32_32x32x16_bf16 v[0:15], v[156:159], v[108:111], v[0:15]
	s_waitcnt lgkmcnt(4)
	v_mfma_f32_32x32x16_bf16 v[16:31], v[160:163], v[108:111], v[16:31]
	s_waitcnt lgkmcnt(2)
	v_mfma_f32_32x32x16_bf16 v[32:47], v[164:167], v[108:111], v[32:47]
	s_waitcnt lgkmcnt(0)
	v_mfma_f32_32x32x16_bf16 v[48:63], v[168:171], v[108:111], v[48:63]
; #define LAS __attribute__((address_space(3)))
; DI int otid() { int t = threadIdx.x; asm volatile("" : "+v"(t)); return t; }
; DI unsigned pk2(float a, float b) { f32x2 v = {a, b}; bf16v2_t r = __builtin_convertvector(v, bf16v2_t); return __builtin_bit_cast(unsigned, r); }
; template <int DQK, int KA8, int DV, bool BIAS, bool JOINT>
; DI void attn_core(LAS unsigned char* lds, const bf16_t* Qrow, const bf16_t* KpA, int ldkA, const bf16_t* KpB, int ldkB, const bf16_t* Vp, int ldv,
;                   int qb, int wid, int lane, const float* qng  , f32x16 (&O)[DV / 32]) {
;     ...
;     l += __shfl_xor(l, 32);
;     const float il = 1.f / l;
; #pragma unroll
;     for (int dt = 0; dt < DV / 32; ++dt) O[dt] *= il;
; }
; DI void phase_attn_a(const Params& p, LAS unsigned char* lds) {
;     const bf16_t* big = (const bf16_t*)(p.ws + ACT); bf16_t* y = (bf16_t*)(p.ws + HBUF); const float* tbg = (const float*)(p.ws + X_BIAS);
;     const int tid = otid(), wid = tid >> 6, lane = tid & 63, l32 = lane & 31, hh = lane >> 5;
;     constexpr int STG = 64 * (64 * 2 + 16 + 128 * 2 + 64);
;     float d0 = 0.f, d1 = 0.f;
;     for (int i = 0; i < 64; ++i) { d0 += p.in[5][i] * p.in[5][64 + i]; d1 += p.in[5][128 + i] * p.in[5][192 + i]; }
;     const float lam_init = 0.2f, lam = __expf(d0) - __expf(d1) + lam_init;
;     for (int pr = blockIdx.x; pr < 512; pr += gridDim.x) {
;         const int bi = pr & 255, bh = (gridDim.x == 256) ? (bi & 7) + 8 * (bi >> 6) + 32 * (pr >> 8) : pr >> 3, j = (gridDim.x == 256) ? (bi >> 3) & 7 : pr & 7, b = bh >> 4, h = bh & 15;
;         for (int half = 0; half < 2; ++half) {
;             const int qb = half ? 15 - j : j;
;             __syncthreads();
;             if (tid < 192) ((LAS float*)(lds + 2 * STG))[tid] = tbg[h * 192 + tid];
;             const size_t tok0 = (size_t)b * SEQ, tokq = tok0 + qb * 256 + wid * 32 + l32;
;             f32x16 Oa[4]; LAS unsigned* Op = (LAS unsigned*)(lds + 2 * STG + 1024) + wid * 2048 + lane;
;             attn_core<64, 8, 128, true, true>(lds, big + tokq * 8192 + h * 128, big + tok0 * 8192 + 2048 + h * 128, 8192, nullptr, 0, big + tok0 * 8192 + 4096 + h * 128, 8192, qb, wid, lane, nullptr, Oa);
; #pragma unroll
;             for (int dt = 0; dt < 4; ++dt)
; #pragma unroll
;                 for (int i = 0; i < 8; ++i) Op[(dt * 8 + i) * 64] = pk2(Oa[dt][2 * i], Oa[dt][2 * i + 1]);
.Laa_nofpv:
	s_cmp_ge_u32 s26, 4
	s_cbranch_scc1 .Laa_noea
	s_barrier
.Laa_noea:
	s_nop 15
	v_mov_b32_e32 v187, v184
	v_mov_b32_e32 v188, v184
	s_nop 1
	v_permlane32_swap_b32_e32 v187, v188
	s_nop 1
	v_add_f32_e32 v184, v187, v188
	v_rcp_f32_e32 v186, v184
	s_nop 1
	v_mul_f32_e32 v0, v0, v186
	v_mul_f32_e32 v1, v1, v186
	v_mul_f32_e32 v2, v2, v186
	v_mul_f32_e32 v3, v3, v186
	v_mul_f32_e32 v4, v4, v186
	v_mul_f32_e32 v5, v5, v186
	v_mul_f32_e32 v6, v6, v186
	v_mul_f32_e32 v7, v7, v186
	v_mul_f32_e32 v8, v8, v186
	v_mul_f32_e32 v9, v9, v186
	v_mul_f32_e32 v10, v10, v186
	v_mul_f32_e32 v11, v11, v186
	v_mul_f32_e32 v12, v12, v186
	v_mul_f32_e32 v13, v13, v186
	v_mul_f32_e32 v14, v14, v186
	v_mul_f32_e32 v15, v15, v186
	v_mul_f32_e32 v16, v16, v186
	v_mul_f32_e32 v17, v17, v186
	v_mul_f32_e32 v18, v18, v186
	v_mul_f32_e32 v19, v19, v186
	v_mul_f32_e32 v20, v20, v186
	v_mul_f32_e32 v21, v21, v186
	v_mul_f32_e32 v22, v22, v186
	v_mul_f32_e32 v23, v23, v186
	v_mul_f32_e32 v24, v24, v186
	v_mul_f32_e32 v25, v25, v186
	v_mul_f32_e32 v26, v26, v186
	v_mul_f32_e32 v27, v27, v186
	v_mul_f32_e32 v28, v28, v186
	v_mul_f32_e32 v29, v29, v186
	v_mul_f32_e32 v30, v30, v186
	v_mul_f32_e32 v31, v31, v186
	v_mul_f32_e32 v32, v32, v186
	v_mul_f32_e32 v33, v33, v186
	v_mul_f32_e32 v34, v34, v186
	v_mul_f32_e32 v35, v35, v186
	v_mul_f32_e32 v36, v36, v186
	v_mul_f32_e32 v37, v37, v186
	v_mul_f32_e32 v38, v38, v186
	v_mul_f32_e32 v39, v39, v186
	v_mul_f32_e32 v40, v40, v186
	v_mul_f32_e32 v41, v41, v186
	v_mul_f32_e32 v42, v42, v186
	v_mul_f32_e32 v43, v43, v186
	v_mul_f32_e32 v44, v44, v186
	v_mul_f32_e32 v45, v45, v186
	v_mul_f32_e32 v46, v46, v186
	v_mul_f32_e32 v47, v47, v186
	v_mul_f32_e32 v48, v48, v186
	v_mul_f32_e32 v49, v49, v186
	v_mul_f32_e32 v50, v50, v186
	v_mul_f32_e32 v51, v51, v186
	v_mul_f32_e32 v52, v52, v186
	v_mul_f32_e32 v53, v53, v186
	v_mul_f32_e32 v54, v54, v186
	v_mul_f32_e32 v55, v55, v186
	v_mul_f32_e32 v56, v56, v186
	v_mul_f32_e32 v57, v57, v186
	v_mul_f32_e32 v58, v58, v186
	v_mul_f32_e32 v59, v59, v186
	v_mul_f32_e32 v60, v60, v186
	v_mul_f32_e32 v61, v61, v186
	v_mul_f32_e32 v62, v62, v186
	v_mul_f32_e32 v63, v63, v186
	s_cmp_eq_u32 s41, 1
	s_cbranch_scc1 .Laa_epi
	v_cvt_pk_bf16_f32 v186, v0, v1
	ds_write_b32 v200, v186 offset:0
	v_cvt_pk_bf16_f32 v187, v2, v3
	ds_write_b32 v200, v187 offset:256
	v_cvt_pk_bf16_f32 v188, v4, v5
	ds_write_b32 v200, v188 offset:512
	v_cvt_pk_bf16_f32 v189, v6, v7
	ds_write_b32 v200, v189 offset:768
	v_cvt_pk_bf16_f32 v186, v8, v9
	ds_write_b32 v200, v186 offset:1024
	v_cvt_pk_bf16_f32 v187, v10, v11
	ds_write_b32 v200, v187 offset:1280
	v_cvt_pk_bf16_f32 v188, v12, v13
	ds_write_b32 v200, v188 offset:1536
	v_cvt_pk_bf16_f32 v189, v14, v15
	ds_write_b32 v200, v189 offset:1792
	v_cvt_pk_bf16_f32 v186, v16, v17
	ds_write_b32 v200, v186 offset:2048
	v_cvt_pk_bf16_f32 v187, v18, v19
	ds_write_b32 v200, v187 offset:2304
	v_cvt_pk_bf16_f32 v188, v20, v21
	ds_write_b32 v200, v188 offset:2560
	v_cvt_pk_bf16_f32 v189, v22, v23
	ds_write_b32 v200, v189 offset:2816
	v_cvt_pk_bf16_f32 v186, v24, v25
	ds_write_b32 v200, v186 offset:3072
	v_cvt_pk_bf16_f32 v187, v26, v27
	ds_write_b32 v200, v187 offset:3328
	v_cvt_pk_bf16_f32 v188, v28, v29
	ds_write_b32 v200, v188 offset:3584
	v_cvt_pk_bf16_f32 v189, v30, v31
	ds_write_b32 v200, v189 offset:3840
	v_cvt_pk_bf16_f32 v186, v32, v33
	ds_write_b32 v200, v186 offset:4096
	v_cvt_pk_bf16_f32 v187, v34, v35
	ds_write_b32 v200, v187 offset:4352
	v_cvt_pk_bf16_f32 v188, v36, v37
	ds_write_b32 v200, v188 offset:4608
	v_cvt_pk_bf16_f32 v189, v38, v39
	ds_write_b32 v200, v189 offset:4864
	v_cvt_pk_bf16_f32 v186, v40, v41
	ds_write_b32 v200, v186 offset:5120
	v_cvt_pk_bf16_f32 v187, v42, v43
	ds_write_b32 v200, v187 offset:5376
	v_cvt_pk_bf16_f32 v188, v44, v45
	ds_write_b32 v200, v188 offset:5632
	v_cvt_pk_bf16_f32 v189, v46, v47
	ds_write_b32 v200, v189 offset:5888
	v_cvt_pk_bf16_f32 v186, v48, v49
	ds_write_b32 v200, v186 offset:6144
	v_cvt_pk_bf16_f32 v187, v50, v51
	ds_write_b32 v200, v187 offset:6400
	v_cvt_pk_bf16_f32 v188, v52, v53
	ds_write_b32 v200, v188 offset:6656
	v_cvt_pk_bf16_f32 v189, v54, v55
	ds_write_b32 v200, v189 offset:6912
	v_cvt_pk_bf16_f32 v186, v56, v57
	ds_write_b32 v200, v186 offset:7168
	v_cvt_pk_bf16_f32 v187, v58, v59
	ds_write_b32 v200, v187 offset:7424
	v_cvt_pk_bf16_f32 v188, v60, v61
	ds_write_b32 v200, v188 offset:7680
	v_cvt_pk_bf16_f32 v189, v62, v63
	ds_write_b32 v200, v189 offset:7936
	s_mov_b32 s41, 1
	s_branch .Laa_pass
; DI void phase_attn_a(const Params& p, LAS unsigned char* lds) {
;     ...
;             float ss = 0.f;
; #pragma unroll
;             for (int dt = 0; dt < 4; ++dt)
; #pragma unroll
;                 for (int i = 0; i < 16; ++i) { const unsigned ow = Op[(dt * 8 + (i >> 1)) * 64]; const float o0 = (i & 1) ? __uint_as_float(ow & 0xffff0000u) : __uint_as_float(ow << 16);
;                     const float o = o0 - lam * Oa[dt][i]; Oa[dt][i] = o; ss += o * o; }
.Laa_epi:
	global_load_dwordx2 v[204:205], v198, s[52:53] offset:0
	global_load_dwordx2 v[206:207], v198, s[52:53] offset:16
	global_load_dwordx2 v[208:209], v198, s[52:53] offset:32
	global_load_dwordx2 v[210:211], v198, s[52:53] offset:48
	global_load_dwordx2 v[212:213], v198, s[52:53] offset:64
	global_load_dwordx2 v[214:215], v198, s[52:53] offset:80
	global_load_dwordx2 v[216:217], v198, s[52:53] offset:96
	global_load_dwordx2 v[218:219], v198, s[52:53] offset:112
	global_load_dwordx2 v[220:221], v198, s[52:53] offset:128
	global_load_dwordx2 v[222:223], v198, s[52:53] offset:144
	global_load_dwordx2 v[224:225], v198, s[52:53] offset:160
	global_load_dwordx2 v[226:227], v198, s[52:53] offset:176
	global_load_dwordx2 v[228:229], v198, s[52:53] offset:192
	global_load_dwordx2 v[230:231], v198, s[52:53] offset:208
	global_load_dwordx2 v[232:233], v198, s[52:53] offset:224
	global_load_dwordx2 v[234:235], v198, s[52:53] offset:240
	ds_read_b32 v140, v200 offset:0
	ds_read_b32 v141, v200 offset:256
	ds_read_b32 v142, v200 offset:512
	ds_read_b32 v143, v200 offset:768
	ds_read_b32 v144, v200 offset:1024
	ds_read_b32 v145, v200 offset:1280
	ds_read_b32 v146, v200 offset:1536
	ds_read_b32 v147, v200 offset:1792
	ds_read_b32 v148, v200 offset:2048
	ds_read_b32 v149, v200 offset:2304
	ds_read_b32 v150, v200 offset:2560
	ds_read_b32 v151, v200 offset:2816
	ds_read_b32 v152, v200 offset:3072
	ds_read_b32 v153, v200 offset:3328
	ds_read_b32 v154, v200 offset:3584
	ds_read_b32 v155, v200 offset:3840
	s_waitcnt lgkmcnt(0)
	v_lshlrev_b32_e32 v186, 16, v140
	v_and_b32_e32 v187, 0xffff0000, v140
	v_fma_f32 v0, -v0, s12, v186
	v_fma_f32 v1, -v1, s12, v187
	v_mul_f32_e32 v189, v0, v0
	v_fmac_f32_e32 v189, v1, v1
	v_lshlrev_b32_e32 v186, 16, v141
	v_and_b32_e32 v187, 0xffff0000, v141
	v_fma_f32 v2, -v2, s12, v186
	v_fma_f32 v3, -v3, s12, v187
	v_fmac_f32_e32 v189, v2, v2
	v_fmac_f32_e32 v189, v3, v3
	v_lshlrev_b32_e32 v186, 16, v142
	v_and_b32_e32 v187, 0xffff0000, v142
	v_fma_f32 v4, -v4, s12, v186
	v_fma_f32 v5, -v5, s12, v187
	v_fmac_f32_e32 v189, v4, v4
	v_fmac_f32_e32 v189, v5, v5
	v_lshlrev_b32_e32 v186, 16, v143
	v_and_b32_e32 v187, 0xffff0000, v143
	v_fma_f32 v6, -v6, s12, v186
	v_fma_f32 v7, -v7, s12, v187
	v_fmac_f32_e32 v189, v6, v6
	v_fmac_f32_e32 v189, v7, v7
	v_lshlrev_b32_e32 v186, 16, v144
	v_and_b32_e32 v187, 0xffff0000, v144
	v_fma_f32 v8, -v8, s12, v186
	v_fma_f32 v9, -v9, s12, v187
	v_fmac_f32_e32 v189, v8, v8
	v_fmac_f32_e32 v189, v9, v9
	v_lshlrev_b32_e32 v186, 16, v145
	v_and_b32_e32 v187, 0xffff0000, v145
	v_fma_f32 v10, -v10, s12, v186
	v_fma_f32 v11, -v11, s12, v187
	v_fmac_f32_e32 v189, v10, v10
	v_fmac_f32_e32 v189, v11, v11
	v_lshlrev_b32_e32 v186, 16, v146
	v_and_b32_e32 v187, 0xffff0000, v146
	v_fma_f32 v12, -v12, s12, v186
	v_fma_f32 v13, -v13, s12, v187
	v_fmac_f32_e32 v189, v12, v12
	v_fmac_f32_e32 v189, v13, v13
	v_lshlrev_b32_e32 v186, 16, v147
	v_and_b32_e32 v187, 0xffff0000, v147
	v_fma_f32 v14, -v14, s12, v186
	v_fma_f32 v15, -v15, s12, v187
	v_fmac_f32_e32 v189, v14, v14
	v_fmac_f32_e32 v189, v15, v15
	v_lshlrev_b32_e32 v186, 16, v148
	v_and_b32_e32 v187, 0xffff0000, v148
	v_fma_f32 v16, -v16, s12, v186
	v_fma_f32 v17, -v17, s12, v187
	v_fmac_f32_e32 v189, v16, v16
	v_fmac_f32_e32 v189, v17, v17
	v_lshlrev_b32_e32 v186, 16, v149
	v_and_b32_e32 v187, 0xffff0000, v149
	v_fma_f32 v18, -v18, s12, v186
	v_fma_f32 v19, -v19, s12, v187
	v_fmac_f32_e32 v189, v18, v18
	v_fmac_f32_e32 v189, v19, v19
	v_lshlrev_b32_e32 v186, 16, v150
	v_and_b32_e32 v187, 0xffff0000, v150
	v_fma_f32 v20, -v20, s12, v186
	v_fma_f32 v21, -v21, s12, v187
	v_fmac_f32_e32 v189, v20, v20
	v_fmac_f32_e32 v189, v21, v21
	v_lshlrev_b32_e32 v186, 16, v151
	v_and_b32_e32 v187, 0xffff0000, v151
	v_fma_f32 v22, -v22, s12, v186
	v_fma_f32 v23, -v23, s12, v187
	v_fmac_f32_e32 v189, v22, v22
	v_fmac_f32_e32 v189, v23, v23
	v_lshlrev_b32_e32 v186, 16, v152
	v_and_b32_e32 v187, 0xffff0000, v152
	v_fma_f32 v24, -v24, s12, v186
	v_fma_f32 v25, -v25, s12, v187
	v_fmac_f32_e32 v189, v24, v24
	v_fmac_f32_e32 v189, v25, v25
	v_lshlrev_b32_e32 v186, 16, v153
	v_and_b32_e32 v187, 0xffff0000, v153
	v_fma_f32 v26, -v26, s12, v186
	v_fma_f32 v27, -v27, s12, v187
	v_fmac_f32_e32 v189, v26, v26
	v_fmac_f32_e32 v189, v27, v27
	v_lshlrev_b32_e32 v186, 16, v154
	v_and_b32_e32 v187, 0xffff0000, v154
	v_fma_f32 v28, -v28, s12, v186
	v_fma_f32 v29, -v29, s12, v187
	v_fmac_f32_e32 v189, v28, v28
	v_fmac_f32_e32 v189, v29, v29
	v_lshlrev_b32_e32 v186, 16, v155
	v_and_b32_e32 v187, 0xffff0000, v155
	v_fma_f32 v30, -v30, s12, v186
	v_fma_f32 v31, -v31, s12, v187
	v_fmac_f32_e32 v189, v30, v30
	v_fmac_f32_e32 v189, v31, v31
	ds_read_b32 v140, v200 offset:4096
	ds_read_b32 v141, v200 offset:4352
	ds_read_b32 v142, v200 offset:4608
	ds_read_b32 v143, v200 offset:4864
	ds_read_b32 v144, v200 offset:5120
	ds_read_b32 v145, v200 offset:5376
	ds_read_b32 v146, v200 offset:5632
	ds_read_b32 v147, v200 offset:5888
	ds_read_b32 v148, v200 offset:6144
	ds_read_b32 v149, v200 offset:6400
	ds_read_b32 v150, v200 offset:6656
	ds_read_b32 v151, v200 offset:6912
	ds_read_b32 v152, v200 offset:7168
	ds_read_b32 v153, v200 offset:7424
	ds_read_b32 v154, v200 offset:7680
	ds_read_b32 v155, v200 offset:7936
	s_waitcnt lgkmcnt(0)
; DI unsigned pk2(float a, float b) { f32x2 v = {a, b}; bf16v2_t r = __builtin_convertvector(v, bf16v2_t); return __builtin_bit_cast(unsigned, r); }
; DI float silu(float x) { return x / (1.f + __expf(-x)); }
; DI void phase_attn_a(const Params& p, LAS unsigned char* lds) {
;     ...
;             float ss = 0.f;
; #pragma unroll
;             for (int dt = 0; dt < 4; ++dt)
; #pragma unroll
;                 for (int i = 0; i < 16; ++i) { const unsigned ow = Op[(dt * 8 + (i >> 1)) * 64]; const float o0 = (i & 1) ? __uint_as_float(ow & 0xffff0000u) : __uint_as_float(ow << 16);
;                     const float o = o0 - lam * Oa[dt][i]; Oa[dt][i] = o; ss += o * o; }
;             ss += __shfl_xor(ss, 32);
;             const float sc = rsqrtf(ss * (1.f / 128.f) + EPS) * (1.f - lam_init);
; #pragma unroll
;             for (int dt = 0; dt < 4; ++dt)
; #pragma unroll
;                 for (int g4 = 0; g4 < 4; ++g4) { const int dv = 32 * dt + 8 * g4 + 4 * hh;
;                     const u32x2 gw = *(const u32x2*)(big + tokq * 8192 + 6144 + h * 128 + dv);
;                     const f32x4 sg = *(const f32x4*)(p.in[6] + dv);
;                     const float g0 = __uint_as_float(gw.x << 16), g1 = __uint_as_float(gw.x & 0xffff0000u), g2 = __uint_as_float(gw.y << 16), g3 = __uint_as_float(gw.y & 0xffff0000u);
;                     u32x2 w; w.x = pk2(Oa[dt][4 * g4] * sc * sg[0] * silu(g0), Oa[dt][4 * g4 + 1] * sc * sg[1] * silu(g1));
;                     w.y = pk2(Oa[dt][4 * g4 + 2] * sc * sg[2] * silu(g2), Oa[dt][4 * g4 + 3] * sc * sg[3] * silu(g3));
;                     *(u32x2*)(y + tokq * DM + h * 128 + dv) = w; }
	v_lshlrev_b32_e32 v186, 16, v140
	v_and_b32_e32 v187, 0xffff0000, v140
	v_fma_f32 v32, -v32, s12, v186
	v_fma_f32 v33, -v33, s12, v187
	v_fmac_f32_e32 v189, v32, v32
	v_fmac_f32_e32 v189, v33, v33
	v_lshlrev_b32_e32 v186, 16, v141
	v_and_b32_e32 v187, 0xffff0000, v141
	v_fma_f32 v34, -v34, s12, v186
	v_fma_f32 v35, -v35, s12, v187
	v_fmac_f32_e32 v189, v34, v34
	v_fmac_f32_e32 v189, v35, v35
	v_lshlrev_b32_e32 v186, 16, v142
	v_and_b32_e32 v187, 0xffff0000, v142
	v_fma_f32 v36, -v36, s12, v186
	v_fma_f32 v37, -v37, s12, v187
	v_fmac_f32_e32 v189, v36, v36
	v_fmac_f32_e32 v189, v37, v37
	v_lshlrev_b32_e32 v186, 16, v143
	v_and_b32_e32 v187, 0xffff0000, v143
	v_fma_f32 v38, -v38, s12, v186
	v_fma_f32 v39, -v39, s12, v187
	v_fmac_f32_e32 v189, v38, v38
	v_fmac_f32_e32 v189, v39, v39
	v_lshlrev_b32_e32 v186, 16, v144
	v_and_b32_e32 v187, 0xffff0000, v144
	v_fma_f32 v40, -v40, s12, v186
	v_fma_f32 v41, -v41, s12, v187
	v_fmac_f32_e32 v189, v40, v40
	v_fmac_f32_e32 v189, v41, v41
	v_lshlrev_b32_e32 v186, 16, v145
	v_and_b32_e32 v187, 0xffff0000, v145
	v_fma_f32 v42, -v42, s12, v186
	v_fma_f32 v43, -v43, s12, v187
	v_fmac_f32_e32 v189, v42, v42
	v_fmac_f32_e32 v189, v43, v43
	v_lshlrev_b32_e32 v186, 16, v146
	v_and_b32_e32 v187, 0xffff0000, v146
	v_fma_f32 v44, -v44, s12, v186
	v_fma_f32 v45, -v45, s12, v187
	v_fmac_f32_e32 v189, v44, v44
	v_fmac_f32_e32 v189, v45, v45
	v_lshlrev_b32_e32 v186, 16, v147
	v_and_b32_e32 v187, 0xffff0000, v147
	v_fma_f32 v46, -v46, s12, v186
	v_fma_f32 v47, -v47, s12, v187
	v_fmac_f32_e32 v189, v46, v46
	v_fmac_f32_e32 v189, v47, v47
	v_lshlrev_b32_e32 v186, 16, v148
	v_and_b32_e32 v187, 0xffff0000, v148
	v_fma_f32 v48, -v48, s12, v186
	v_fma_f32 v49, -v49, s12, v187
	v_fmac_f32_e32 v189, v48, v48
	v_fmac_f32_e32 v189, v49, v49
	v_lshlrev_b32_e32 v186, 16, v149
	v_and_b32_e32 v187, 0xffff0000, v149
	v_fma_f32 v50, -v50, s12, v186
	v_fma_f32 v51, -v51, s12, v187
	v_fmac_f32_e32 v189, v50, v50
	v_fmac_f32_e32 v189, v51, v51
	v_lshlrev_b32_e32 v186, 16, v150
	v_and_b32_e32 v187, 0xffff0000, v150
	v_fma_f32 v52, -v52, s12, v186
	v_fma_f32 v53, -v53, s12, v187
	v_fmac_f32_e32 v189, v52, v52
	v_fmac_f32_e32 v189, v53, v53
	v_lshlrev_b32_e32 v186, 16, v151
	v_and_b32_e32 v187, 0xffff0000, v151
	v_fma_f32 v54, -v54, s12, v186
	v_fma_f32 v55, -v55, s12, v187
	v_fmac_f32_e32 v189, v54, v54
	v_fmac_f32_e32 v189, v55, v55
	v_lshlrev_b32_e32 v186, 16, v152
	v_and_b32_e32 v187, 0xffff0000, v152
	v_fma_f32 v56, -v56, s12, v186
	v_fma_f32 v57, -v57, s12, v187
	v_fmac_f32_e32 v189, v56, v56
	v_fmac_f32_e32 v189, v57, v57
	v_lshlrev_b32_e32 v186, 16, v153
	v_and_b32_e32 v187, 0xffff0000, v153
	v_fma_f32 v58, -v58, s12, v186
	v_fma_f32 v59, -v59, s12, v187
	v_fmac_f32_e32 v189, v58, v58
	v_fmac_f32_e32 v189, v59, v59
	v_lshlrev_b32_e32 v186, 16, v154
	v_and_b32_e32 v187, 0xffff0000, v154
	v_fma_f32 v60, -v60, s12, v186
	v_fma_f32 v61, -v61, s12, v187
	v_fmac_f32_e32 v189, v60, v60
	v_fmac_f32_e32 v189, v61, v61
	v_lshlrev_b32_e32 v186, 16, v155
	v_and_b32_e32 v187, 0xffff0000, v155
	v_fma_f32 v62, -v62, s12, v186
	v_fma_f32 v63, -v63, s12, v187
	v_fmac_f32_e32 v189, v62, v62
	v_fmac_f32_e32 v189, v63, v63
	v_mov_b32_e32 v187, v189
	v_mov_b32_e32 v188, v189
	s_nop 1
	v_permlane32_swap_b32_e32 v187, v188
	s_nop 1
	v_add_f32_e32 v189, v187, v188
	v_mul_f32_e32 v189, 0x3c000000, v189
	v_add_f32_e32 v189, 0x358637bd, v189
	v_rsq_f32_e32 v189, v189
	s_nop 1
	v_mul_f32_e32 v189, 0x3f4ccccd, v189
	ds_read_b128 v[140:143], v201 offset:0
	ds_read_b128 v[144:147], v201 offset:32
	ds_read_b128 v[148:151], v201 offset:64
	ds_read_b128 v[152:155], v201 offset:96
	s_waitcnt vmcnt(0)
	s_waitcnt lgkmcnt(0)
	v_lshlrev_b32_e32 v156, 16, v204
	v_and_b32_e32 v157, 0xffff0000, v204
	v_lshlrev_b32_e32 v158, 16, v205
	v_and_b32_e32 v159, 0xffff0000, v205
	v_mul_f32_e32 v164, 0xbfb8aa3b, v156
	v_mul_f32_e32 v165, 0xbfb8aa3b, v157
	v_mul_f32_e32 v166, 0xbfb8aa3b, v158
	v_mul_f32_e32 v167, 0xbfb8aa3b, v159
	v_exp_f32_e32 v164, v164
	v_exp_f32_e32 v165, v165
	v_exp_f32_e32 v166, v166
	v_exp_f32_e32 v167, v167
	v_mul_f32_e32 v0, v0, v189
	v_mul_f32_e32 v1, v1, v189
	v_mul_f32_e32 v2, v2, v189
	v_mul_f32_e32 v3, v3, v189
	v_add_f32_e32 v164, 1.0, v164
	v_add_f32_e32 v165, 1.0, v165
	v_add_f32_e32 v166, 1.0, v166
	v_add_f32_e32 v167, 1.0, v167
	v_rcp_f32_e32 v164, v164
	v_rcp_f32_e32 v165, v165
	v_rcp_f32_e32 v166, v166
	v_rcp_f32_e32 v167, v167
	v_mul_f32_e32 v0, v0, v140
	v_mul_f32_e32 v1, v1, v141
	v_mul_f32_e32 v2, v2, v142
	v_mul_f32_e32 v3, v3, v143
	v_mul_f32_e32 v156, v156, v164
	v_mul_f32_e32 v157, v157, v165
	v_mul_f32_e32 v158, v158, v166
	v_mul_f32_e32 v159, v159, v167
	v_mul_f32_e32 v0, v0, v156
	v_mul_f32_e32 v1, v1, v157
	v_mul_f32_e32 v2, v2, v158
	v_mul_f32_e32 v3, v3, v159
	v_cvt_pk_bf16_f32 v204, v0, v1
	v_cvt_pk_bf16_f32 v205, v2, v3
	global_store_dwordx2 v199, v[204:205], s[54:55] offset:0
	v_lshlrev_b32_e32 v160, 16, v206
	v_and_b32_e32 v161, 0xffff0000, v206
	v_lshlrev_b32_e32 v162, 16, v207
	v_and_b32_e32 v163, 0xffff0000, v207
	v_mul_f32_e32 v168, 0xbfb8aa3b, v160
	v_mul_f32_e32 v169, 0xbfb8aa3b, v161
	v_mul_f32_e32 v170, 0xbfb8aa3b, v162
	v_mul_f32_e32 v171, 0xbfb8aa3b, v163
	v_exp_f32_e32 v168, v168
	v_exp_f32_e32 v169, v169
	v_exp_f32_e32 v170, v170
	v_exp_f32_e32 v171, v171
	v_mul_f32_e32 v4, v4, v189
	v_mul_f32_e32 v5, v5, v189
	v_mul_f32_e32 v6, v6, v189
	v_mul_f32_e32 v7, v7, v189
	v_add_f32_e32 v168, 1.0, v168
	v_add_f32_e32 v169, 1.0, v169
	v_add_f32_e32 v170, 1.0, v170
	v_add_f32_e32 v171, 1.0, v171
	v_rcp_f32_e32 v168, v168
	v_rcp_f32_e32 v169, v169
	v_rcp_f32_e32 v170, v170
	v_rcp_f32_e32 v171, v171
	v_mul_f32_e32 v4, v4, v144
; DI unsigned pk2(float a, float b) { f32x2 v = {a, b}; bf16v2_t r = __builtin_convertvector(v, bf16v2_t); return __builtin_bit_cast(unsigned, r); }
; DI float silu(float x) { return x / (1.f + __expf(-x)); }
; DI void phase_attn_a(const Params& p, LAS unsigned char* lds) {
;     ...
; #pragma unroll
;             for (int dt = 0; dt < 4; ++dt)
; #pragma unroll
;                 for (int g4 = 0; g4 < 4; ++g4) { const int dv = 32 * dt + 8 * g4 + 4 * hh;
;                     const u32x2 gw = *(const u32x2*)(big + tokq * 8192 + 6144 + h * 128 + dv);
;                     const f32x4 sg = *(const f32x4*)(p.in[6] + dv);
;                     const float g0 = __uint_as_float(gw.x << 16), g1 = __uint_as_float(gw.x & 0xffff0000u), g2 = __uint_as_float(gw.y << 16), g3 = __uint_as_float(gw.y & 0xffff0000u);
;                     u32x2 w; w.x = pk2(Oa[dt][4 * g4] * sc * sg[0] * silu(g0), Oa[dt][4 * g4 + 1] * sc * sg[1] * silu(g1));
;                     w.y = pk2(Oa[dt][4 * g4 + 2] * sc * sg[2] * silu(g2), Oa[dt][4 * g4 + 3] * sc * sg[3] * silu(g3));
;                     *(u32x2*)(y + tokq * DM + h * 128 + dv) = w; }
	v_mul_f32_e32 v5, v5, v145
	v_mul_f32_e32 v6, v6, v146
	v_mul_f32_e32 v7, v7, v147
	v_mul_f32_e32 v160, v160, v168
	v_mul_f32_e32 v161, v161, v169
	v_mul_f32_e32 v162, v162, v170
	v_mul_f32_e32 v163, v163, v171
	v_mul_f32_e32 v4, v4, v160
	v_mul_f32_e32 v5, v5, v161
	v_mul_f32_e32 v6, v6, v162
	v_mul_f32_e32 v7, v7, v163
	v_cvt_pk_bf16_f32 v206, v4, v5
	v_cvt_pk_bf16_f32 v207, v6, v7
	global_store_dwordx2 v199, v[206:207], s[54:55] offset:16
	v_lshlrev_b32_e32 v156, 16, v208
	v_and_b32_e32 v157, 0xffff0000, v208
	v_lshlrev_b32_e32 v158, 16, v209
	v_and_b32_e32 v159, 0xffff0000, v209
	v_mul_f32_e32 v164, 0xbfb8aa3b, v156
	v_mul_f32_e32 v165, 0xbfb8aa3b, v157
	v_mul_f32_e32 v166, 0xbfb8aa3b, v158
	v_mul_f32_e32 v167, 0xbfb8aa3b, v159
	v_exp_f32_e32 v164, v164
	v_exp_f32_e32 v165, v165
	v_exp_f32_e32 v166, v166
	v_exp_f32_e32 v167, v167
	v_mul_f32_e32 v8, v8, v189
	v_mul_f32_e32 v9, v9, v189
	v_mul_f32_e32 v10, v10, v189
	v_mul_f32_e32 v11, v11, v189
	v_add_f32_e32 v164, 1.0, v164
	v_add_f32_e32 v165, 1.0, v165
	v_add_f32_e32 v166, 1.0, v166
	v_add_f32_e32 v167, 1.0, v167
	v_rcp_f32_e32 v164, v164
	v_rcp_f32_e32 v165, v165
	v_rcp_f32_e32 v166, v166
	v_rcp_f32_e32 v167, v167
	v_mul_f32_e32 v8, v8, v148
	v_mul_f32_e32 v9, v9, v149
	v_mul_f32_e32 v10, v10, v150
	v_mul_f32_e32 v11, v11, v151
	v_mul_f32_e32 v156, v156, v164
	v_mul_f32_e32 v157, v157, v165
	v_mul_f32_e32 v158, v158, v166
	v_mul_f32_e32 v159, v159, v167
	v_mul_f32_e32 v8, v8, v156
	v_mul_f32_e32 v9, v9, v157
	v_mul_f32_e32 v10, v10, v158
	v_mul_f32_e32 v11, v11, v159
	v_cvt_pk_bf16_f32 v208, v8, v9
	v_cvt_pk_bf16_f32 v209, v10, v11
	global_store_dwordx2 v199, v[208:209], s[54:55] offset:32
	v_lshlrev_b32_e32 v160, 16, v210
	v_and_b32_e32 v161, 0xffff0000, v210
	v_lshlrev_b32_e32 v162, 16, v211
	v_and_b32_e32 v163, 0xffff0000, v211
	v_mul_f32_e32 v168, 0xbfb8aa3b, v160
	v_mul_f32_e32 v169, 0xbfb8aa3b, v161
	v_mul_f32_e32 v170, 0xbfb8aa3b, v162
	v_mul_f32_e32 v171, 0xbfb8aa3b, v163
	v_exp_f32_e32 v168, v168
	v_exp_f32_e32 v169, v169
	v_exp_f32_e32 v170, v170
	v_exp_f32_e32 v171, v171
	v_mul_f32_e32 v12, v12, v189
	v_mul_f32_e32 v13, v13, v189
	v_mul_f32_e32 v14, v14, v189
	v_mul_f32_e32 v15, v15, v189
	v_add_f32_e32 v168, 1.0, v168
	v_add_f32_e32 v169, 1.0, v169
	v_add_f32_e32 v170, 1.0, v170
	v_add_f32_e32 v171, 1.0, v171
	v_rcp_f32_e32 v168, v168
	v_rcp_f32_e32 v169, v169
	v_rcp_f32_e32 v170, v170
	v_rcp_f32_e32 v171, v171
	v_mul_f32_e32 v12, v12, v152
	v_mul_f32_e32 v13, v13, v153
	v_mul_f32_e32 v14, v14, v154
	v_mul_f32_e32 v15, v15, v155
	v_mul_f32_e32 v160, v160, v168
	v_mul_f32_e32 v161, v161, v169
	v_mul_f32_e32 v162, v162, v170
	v_mul_f32_e32 v163, v163, v171
	v_mul_f32_e32 v12, v12, v160
	v_mul_f32_e32 v13, v13, v161
	v_mul_f32_e32 v14, v14, v162
	v_mul_f32_e32 v15, v15, v163
	v_cvt_pk_bf16_f32 v210, v12, v13
	v_cvt_pk_bf16_f32 v211, v14, v15
	global_store_dwordx2 v199, v[210:211], s[54:55] offset:48
	ds_read_b128 v[140:143], v201 offset:128
	ds_read_b128 v[144:147], v201 offset:160
	ds_read_b128 v[148:151], v201 offset:192
	ds_read_b128 v[152:155], v201 offset:224
	s_waitcnt lgkmcnt(0)
	v_lshlrev_b32_e32 v156, 16, v212
	v_and_b32_e32 v157, 0xffff0000, v212
	v_lshlrev_b32_e32 v158, 16, v213
	v_and_b32_e32 v159, 0xffff0000, v213
	v_mul_f32_e32 v164, 0xbfb8aa3b, v156
	v_mul_f32_e32 v165, 0xbfb8aa3b, v157
	v_mul_f32_e32 v166, 0xbfb8aa3b, v158
	v_mul_f32_e32 v167, 0xbfb8aa3b, v159
	v_exp_f32_e32 v164, v164
	v_exp_f32_e32 v165, v165
	v_exp_f32_e32 v166, v166
	v_exp_f32_e32 v167, v167
	v_mul_f32_e32 v16, v16, v189
	v_mul_f32_e32 v17, v17, v189
	v_mul_f32_e32 v18, v18, v189
	v_mul_f32_e32 v19, v19, v189
	v_add_f32_e32 v164, 1.0, v164
	v_add_f32_e32 v165, 1.0, v165
	v_add_f32_e32 v166, 1.0, v166
	v_add_f32_e32 v167, 1.0, v167
	v_rcp_f32_e32 v164, v164
	v_rcp_f32_e32 v165, v165
	v_rcp_f32_e32 v166, v166
	v_rcp_f32_e32 v167, v167
	v_mul_f32_e32 v16, v16, v140
	v_mul_f32_e32 v17, v17, v141
	v_mul_f32_e32 v18, v18, v142
	v_mul_f32_e32 v19, v19, v143
	v_mul_f32_e32 v156, v156, v164
	v_mul_f32_e32 v157, v157, v165
	v_mul_f32_e32 v158, v158, v166
	v_mul_f32_e32 v159, v159, v167
	v_mul_f32_e32 v16, v16, v156
	v_mul_f32_e32 v17, v17, v157
	v_mul_f32_e32 v18, v18, v158
	v_mul_f32_e32 v19, v19, v159
	v_cvt_pk_bf16_f32 v212, v16, v17
	v_cvt_pk_bf16_f32 v213, v18, v19
	global_store_dwordx2 v199, v[212:213], s[54:55] offset:64
	v_lshlrev_b32_e32 v160, 16, v214
	v_and_b32_e32 v161, 0xffff0000, v214
	v_lshlrev_b32_e32 v162, 16, v215
	v_and_b32_e32 v163, 0xffff0000, v215
	v_mul_f32_e32 v168, 0xbfb8aa3b, v160
	v_mul_f32_e32 v169, 0xbfb8aa3b, v161
	v_mul_f32_e32 v170, 0xbfb8aa3b, v162
	v_mul_f32_e32 v171, 0xbfb8aa3b, v163
	v_exp_f32_e32 v168, v168
	v_exp_f32_e32 v169, v169
	v_exp_f32_e32 v170, v170
	v_exp_f32_e32 v171, v171
	v_mul_f32_e32 v20, v20, v189
	v_mul_f32_e32 v21, v21, v189
	v_mul_f32_e32 v22, v22, v189
	v_mul_f32_e32 v23, v23, v189
	v_add_f32_e32 v168, 1.0, v168
	v_add_f32_e32 v169, 1.0, v169
	v_add_f32_e32 v170, 1.0, v170
	v_add_f32_e32 v171, 1.0, v171
	v_rcp_f32_e32 v168, v168
	v_rcp_f32_e32 v169, v169
	v_rcp_f32_e32 v170, v170
	v_rcp_f32_e32 v171, v171
	v_mul_f32_e32 v20, v20, v144
	v_mul_f32_e32 v21, v21, v145
	v_mul_f32_e32 v22, v22, v146
	v_mul_f32_e32 v23, v23, v147
	v_mul_f32_e32 v160, v160, v168
	v_mul_f32_e32 v161, v161, v169
	v_mul_f32_e32 v162, v162, v170
	v_mul_f32_e32 v163, v163, v171
	v_mul_f32_e32 v20, v20, v160
	v_mul_f32_e32 v21, v21, v161
	v_mul_f32_e32 v22, v22, v162
	v_mul_f32_e32 v23, v23, v163
	v_cvt_pk_bf16_f32 v214, v20, v21
	v_cvt_pk_bf16_f32 v215, v22, v23
	global_store_dwordx2 v199, v[214:215], s[54:55] offset:80
	v_lshlrev_b32_e32 v156, 16, v216
; DI unsigned pk2(float a, float b) { f32x2 v = {a, b}; bf16v2_t r = __builtin_convertvector(v, bf16v2_t); return __builtin_bit_cast(unsigned, r); }
; DI float silu(float x) { return x / (1.f + __expf(-x)); }
; DI void phase_attn_a(const Params& p, LAS unsigned char* lds) {
;     ...
; #pragma unroll
;             for (int dt = 0; dt < 4; ++dt)
; #pragma unroll
;                 for (int g4 = 0; g4 < 4; ++g4) { const int dv = 32 * dt + 8 * g4 + 4 * hh;
;                     const u32x2 gw = *(const u32x2*)(big + tokq * 8192 + 6144 + h * 128 + dv);
;                     const f32x4 sg = *(const f32x4*)(p.in[6] + dv);
;                     const float g0 = __uint_as_float(gw.x << 16), g1 = __uint_as_float(gw.x & 0xffff0000u), g2 = __uint_as_float(gw.y << 16), g3 = __uint_as_float(gw.y & 0xffff0000u);
;                     u32x2 w; w.x = pk2(Oa[dt][4 * g4] * sc * sg[0] * silu(g0), Oa[dt][4 * g4 + 1] * sc * sg[1] * silu(g1));
;                     w.y = pk2(Oa[dt][4 * g4 + 2] * sc * sg[2] * silu(g2), Oa[dt][4 * g4 + 3] * sc * sg[3] * silu(g3));
;                     *(u32x2*)(y + tokq * DM + h * 128 + dv) = w; }
	v_and_b32_e32 v157, 0xffff0000, v216
	v_lshlrev_b32_e32 v158, 16, v217
	v_and_b32_e32 v159, 0xffff0000, v217
	v_mul_f32_e32 v164, 0xbfb8aa3b, v156
	v_mul_f32_e32 v165, 0xbfb8aa3b, v157
	v_mul_f32_e32 v166, 0xbfb8aa3b, v158
	v_mul_f32_e32 v167, 0xbfb8aa3b, v159
	v_exp_f32_e32 v164, v164
	v_exp_f32_e32 v165, v165
	v_exp_f32_e32 v166, v166
	v_exp_f32_e32 v167, v167
	v_mul_f32_e32 v24, v24, v189
	v_mul_f32_e32 v25, v25, v189
	v_mul_f32_e32 v26, v26, v189
	v_mul_f32_e32 v27, v27, v189
	v_add_f32_e32 v164, 1.0, v164
	v_add_f32_e32 v165, 1.0, v165
	v_add_f32_e32 v166, 1.0, v166
	v_add_f32_e32 v167, 1.0, v167
	v_rcp_f32_e32 v164, v164
	v_rcp_f32_e32 v165, v165
	v_rcp_f32_e32 v166, v166
	v_rcp_f32_e32 v167, v167
	v_mul_f32_e32 v24, v24, v148
	v_mul_f32_e32 v25, v25, v149
	v_mul_f32_e32 v26, v26, v150
	v_mul_f32_e32 v27, v27, v151
	v_mul_f32_e32 v156, v156, v164
	v_mul_f32_e32 v157, v157, v165
	v_mul_f32_e32 v158, v158, v166
	v_mul_f32_e32 v159, v159, v167
	v_mul_f32_e32 v24, v24, v156
	v_mul_f32_e32 v25, v25, v157
	v_mul_f32_e32 v26, v26, v158
	v_mul_f32_e32 v27, v27, v159
	v_cvt_pk_bf16_f32 v216, v24, v25
	v_cvt_pk_bf16_f32 v217, v26, v27
	global_store_dwordx2 v199, v[216:217], s[54:55] offset:96
	v_lshlrev_b32_e32 v160, 16, v218
	v_and_b32_e32 v161, 0xffff0000, v218
	v_lshlrev_b32_e32 v162, 16, v219
	v_and_b32_e32 v163, 0xffff0000, v219
	v_mul_f32_e32 v168, 0xbfb8aa3b, v160
	v_mul_f32_e32 v169, 0xbfb8aa3b, v161
	v_mul_f32_e32 v170, 0xbfb8aa3b, v162
	v_mul_f32_e32 v171, 0xbfb8aa3b, v163
	v_exp_f32_e32 v168, v168
	v_exp_f32_e32 v169, v169
	v_exp_f32_e32 v170, v170
	v_exp_f32_e32 v171, v171
	v_mul_f32_e32 v28, v28, v189
	v_mul_f32_e32 v29, v29, v189
	v_mul_f32_e32 v30, v30, v189
	v_mul_f32_e32 v31, v31, v189
	v_add_f32_e32 v168, 1.0, v168
	v_add_f32_e32 v169, 1.0, v169
	v_add_f32_e32 v170, 1.0, v170
	v_add_f32_e32 v171, 1.0, v171
	v_rcp_f32_e32 v168, v168
	v_rcp_f32_e32 v169, v169
	v_rcp_f32_e32 v170, v170
	v_rcp_f32_e32 v171, v171
	v_mul_f32_e32 v28, v28, v152
	v_mul_f32_e32 v29, v29, v153
	v_mul_f32_e32 v30, v30, v154
	v_mul_f32_e32 v31, v31, v155
	v_mul_f32_e32 v160, v160, v168
	v_mul_f32_e32 v161, v161, v169
	v_mul_f32_e32 v162, v162, v170
	v_mul_f32_e32 v163, v163, v171
	v_mul_f32_e32 v28, v28, v160
	v_mul_f32_e32 v29, v29, v161
	v_mul_f32_e32 v30, v30, v162
	v_mul_f32_e32 v31, v31, v163
	v_cvt_pk_bf16_f32 v218, v28, v29
	v_cvt_pk_bf16_f32 v219, v30, v31
	global_store_dwordx2 v199, v[218:219], s[54:55] offset:112
	ds_read_b128 v[140:143], v201 offset:256
	ds_read_b128 v[144:147], v201 offset:288
	ds_read_b128 v[148:151], v201 offset:320
	ds_read_b128 v[152:155], v201 offset:352
	s_waitcnt lgkmcnt(0)
	v_lshlrev_b32_e32 v156, 16, v220
	v_and_b32_e32 v157, 0xffff0000, v220
	v_lshlrev_b32_e32 v158, 16, v221
	v_and_b32_e32 v159, 0xffff0000, v221
	v_mul_f32_e32 v164, 0xbfb8aa3b, v156
	v_mul_f32_e32 v165, 0xbfb8aa3b, v157
	v_mul_f32_e32 v166, 0xbfb8aa3b, v158
	v_mul_f32_e32 v167, 0xbfb8aa3b, v159
	v_exp_f32_e32 v164, v164
	v_exp_f32_e32 v165, v165
	v_exp_f32_e32 v166, v166
	v_exp_f32_e32 v167, v167
	v_mul_f32_e32 v32, v32, v189
	v_mul_f32_e32 v33, v33, v189
	v_mul_f32_e32 v34, v34, v189
	v_mul_f32_e32 v35, v35, v189
	v_add_f32_e32 v164, 1.0, v164
	v_add_f32_e32 v165, 1.0, v165
	v_add_f32_e32 v166, 1.0, v166
	v_add_f32_e32 v167, 1.0, v167
	v_rcp_f32_e32 v164, v164
	v_rcp_f32_e32 v165, v165
	v_rcp_f32_e32 v166, v166
	v_rcp_f32_e32 v167, v167
	v_mul_f32_e32 v32, v32, v140
	v_mul_f32_e32 v33, v33, v141
	v_mul_f32_e32 v34, v34, v142
	v_mul_f32_e32 v35, v35, v143
	v_mul_f32_e32 v156, v156, v164
	v_mul_f32_e32 v157, v157, v165
	v_mul_f32_e32 v158, v158, v166
	v_mul_f32_e32 v159, v159, v167
	v_mul_f32_e32 v32, v32, v156
	v_mul_f32_e32 v33, v33, v157
	v_mul_f32_e32 v34, v34, v158
	v_mul_f32_e32 v35, v35, v159
	v_cvt_pk_bf16_f32 v220, v32, v33
	v_cvt_pk_bf16_f32 v221, v34, v35
	global_store_dwordx2 v199, v[220:221], s[54:55] offset:128
	v_lshlrev_b32_e32 v160, 16, v222
	v_and_b32_e32 v161, 0xffff0000, v222
	v_lshlrev_b32_e32 v162, 16, v223
	v_and_b32_e32 v163, 0xffff0000, v223
	v_mul_f32_e32 v168, 0xbfb8aa3b, v160
	v_mul_f32_e32 v169, 0xbfb8aa3b, v161
	v_mul_f32_e32 v170, 0xbfb8aa3b, v162
	v_mul_f32_e32 v171, 0xbfb8aa3b, v163
	v_exp_f32_e32 v168, v168
	v_exp_f32_e32 v169, v169
	v_exp_f32_e32 v170, v170
	v_exp_f32_e32 v171, v171
	v_mul_f32_e32 v36, v36, v189
	v_mul_f32_e32 v37, v37, v189
	v_mul_f32_e32 v38, v38, v189
	v_mul_f32_e32 v39, v39, v189
	v_add_f32_e32 v168, 1.0, v168
	v_add_f32_e32 v169, 1.0, v169
	v_add_f32_e32 v170, 1.0, v170
	v_add_f32_e32 v171, 1.0, v171
	v_rcp_f32_e32 v168, v168
	v_rcp_f32_e32 v169, v169
	v_rcp_f32_e32 v170, v170
	v_rcp_f32_e32 v171, v171
	v_mul_f32_e32 v36, v36, v144
	v_mul_f32_e32 v37, v37, v145
	v_mul_f32_e32 v38, v38, v146
	v_mul_f32_e32 v39, v39, v147
	v_mul_f32_e32 v160, v160, v168
	v_mul_f32_e32 v161, v161, v169
	v_mul_f32_e32 v162, v162, v170
	v_mul_f32_e32 v163, v163, v171
	v_mul_f32_e32 v36, v36, v160
	v_mul_f32_e32 v37, v37, v161
	v_mul_f32_e32 v38, v38, v162
	v_mul_f32_e32 v39, v39, v163
	v_cvt_pk_bf16_f32 v222, v36, v37
	v_cvt_pk_bf16_f32 v223, v38, v39
	global_store_dwordx2 v199, v[222:223], s[54:55] offset:144
	v_lshlrev_b32_e32 v156, 16, v224
	v_and_b32_e32 v157, 0xffff0000, v224
	v_lshlrev_b32_e32 v158, 16, v225
	v_and_b32_e32 v159, 0xffff0000, v225
	v_mul_f32_e32 v164, 0xbfb8aa3b, v156
	v_mul_f32_e32 v165, 0xbfb8aa3b, v157
	v_mul_f32_e32 v166, 0xbfb8aa3b, v158
	v_mul_f32_e32 v167, 0xbfb8aa3b, v159
	v_exp_f32_e32 v164, v164
	v_exp_f32_e32 v165, v165
	v_exp_f32_e32 v166, v166
	v_exp_f32_e32 v167, v167
	v_mul_f32_e32 v40, v40, v189
	v_mul_f32_e32 v41, v41, v189
	v_mul_f32_e32 v42, v42, v189
	v_mul_f32_e32 v43, v43, v189
; DI unsigned pk2(float a, float b) { f32x2 v = {a, b}; bf16v2_t r = __builtin_convertvector(v, bf16v2_t); return __builtin_bit_cast(unsigned, r); }
; DI float silu(float x) { return x / (1.f + __expf(-x)); }
; DI void phase_attn_a(const Params& p, LAS unsigned char* lds) {
;     ...
; #pragma unroll
;             for (int dt = 0; dt < 4; ++dt)
; #pragma unroll
;                 for (int g4 = 0; g4 < 4; ++g4) { const int dv = 32 * dt + 8 * g4 + 4 * hh;
;                     const u32x2 gw = *(const u32x2*)(big + tokq * 8192 + 6144 + h * 128 + dv);
;                     const f32x4 sg = *(const f32x4*)(p.in[6] + dv);
;                     const float g0 = __uint_as_float(gw.x << 16), g1 = __uint_as_float(gw.x & 0xffff0000u), g2 = __uint_as_float(gw.y << 16), g3 = __uint_as_float(gw.y & 0xffff0000u);
;                     u32x2 w; w.x = pk2(Oa[dt][4 * g4] * sc * sg[0] * silu(g0), Oa[dt][4 * g4 + 1] * sc * sg[1] * silu(g1));
;                     w.y = pk2(Oa[dt][4 * g4 + 2] * sc * sg[2] * silu(g2), Oa[dt][4 * g4 + 3] * sc * sg[3] * silu(g3));
;                     *(u32x2*)(y + tokq * DM + h * 128 + dv) = w; }
	v_add_f32_e32 v164, 1.0, v164
	v_add_f32_e32 v165, 1.0, v165
	v_add_f32_e32 v166, 1.0, v166
	v_add_f32_e32 v167, 1.0, v167
	v_rcp_f32_e32 v164, v164
	v_rcp_f32_e32 v165, v165
	v_rcp_f32_e32 v166, v166
	v_rcp_f32_e32 v167, v167
	v_mul_f32_e32 v40, v40, v148
	v_mul_f32_e32 v41, v41, v149
	v_mul_f32_e32 v42, v42, v150
	v_mul_f32_e32 v43, v43, v151
	v_mul_f32_e32 v156, v156, v164
	v_mul_f32_e32 v157, v157, v165
	v_mul_f32_e32 v158, v158, v166
	v_mul_f32_e32 v159, v159, v167
	v_mul_f32_e32 v40, v40, v156
	v_mul_f32_e32 v41, v41, v157
	v_mul_f32_e32 v42, v42, v158
	v_mul_f32_e32 v43, v43, v159
	v_cvt_pk_bf16_f32 v224, v40, v41
	v_cvt_pk_bf16_f32 v225, v42, v43
	global_store_dwordx2 v199, v[224:225], s[54:55] offset:160
	v_lshlrev_b32_e32 v160, 16, v226
	v_and_b32_e32 v161, 0xffff0000, v226
	v_lshlrev_b32_e32 v162, 16, v227
	v_and_b32_e32 v163, 0xffff0000, v227
	v_mul_f32_e32 v168, 0xbfb8aa3b, v160
	v_mul_f32_e32 v169, 0xbfb8aa3b, v161
	v_mul_f32_e32 v170, 0xbfb8aa3b, v162
	v_mul_f32_e32 v171, 0xbfb8aa3b, v163
	v_exp_f32_e32 v168, v168
	v_exp_f32_e32 v169, v169
	v_exp_f32_e32 v170, v170
	v_exp_f32_e32 v171, v171
	v_mul_f32_e32 v44, v44, v189
	v_mul_f32_e32 v45, v45, v189
	v_mul_f32_e32 v46, v46, v189
	v_mul_f32_e32 v47, v47, v189
	v_add_f32_e32 v168, 1.0, v168
	v_add_f32_e32 v169, 1.0, v169
	v_add_f32_e32 v170, 1.0, v170
	v_add_f32_e32 v171, 1.0, v171
	v_rcp_f32_e32 v168, v168
	v_rcp_f32_e32 v169, v169
	v_rcp_f32_e32 v170, v170
	v_rcp_f32_e32 v171, v171
	v_mul_f32_e32 v44, v44, v152
	v_mul_f32_e32 v45, v45, v153
	v_mul_f32_e32 v46, v46, v154
	v_mul_f32_e32 v47, v47, v155
	v_mul_f32_e32 v160, v160, v168
	v_mul_f32_e32 v161, v161, v169
	v_mul_f32_e32 v162, v162, v170
	v_mul_f32_e32 v163, v163, v171
	v_mul_f32_e32 v44, v44, v160
	v_mul_f32_e32 v45, v45, v161
	v_mul_f32_e32 v46, v46, v162
	v_mul_f32_e32 v47, v47, v163
	v_cvt_pk_bf16_f32 v226, v44, v45
	v_cvt_pk_bf16_f32 v227, v46, v47
	global_store_dwordx2 v199, v[226:227], s[54:55] offset:176
	ds_read_b128 v[140:143], v201 offset:384
	ds_read_b128 v[144:147], v201 offset:416
	ds_read_b128 v[148:151], v201 offset:448
	ds_read_b128 v[152:155], v201 offset:480
	s_waitcnt lgkmcnt(0)
; DI unsigned pk2(float a, float b) { f32x2 v = {a, b}; bf16v2_t r = __builtin_convertvector(v, bf16v2_t); return __builtin_bit_cast(unsigned, r); }
; DI float silu(float x) { return x / (1.f + __expf(-x)); }
; DI void phase_attn_a(const Params& p, LAS unsigned char* lds) {
;     ...
; #pragma unroll
;             for (int dt = 0; dt < 4; ++dt)
; #pragma unroll
;                 for (int g4 = 0; g4 < 4; ++g4) { const int dv = 32 * dt + 8 * g4 + 4 * hh;
;                     const u32x2 gw = *(const u32x2*)(big + tokq * 8192 + 6144 + h * 128 + dv);
;                     const f32x4 sg = *(const f32x4*)(p.in[6] + dv);
;                     const float g0 = __uint_as_float(gw.x << 16), g1 = __uint_as_float(gw.x & 0xffff0000u), g2 = __uint_as_float(gw.y << 16), g3 = __uint_as_float(gw.y & 0xffff0000u);
;                     u32x2 w; w.x = pk2(Oa[dt][4 * g4] * sc * sg[0] * silu(g0), Oa[dt][4 * g4 + 1] * sc * sg[1] * silu(g1));
;                     w.y = pk2(Oa[dt][4 * g4 + 2] * sc * sg[2] * silu(g2), Oa[dt][4 * g4 + 3] * sc * sg[3] * silu(g3));
;                     *(u32x2*)(y + tokq * DM + h * 128 + dv) = w; }
;         }
;     }
	v_lshlrev_b32_e32 v156, 16, v228
	v_and_b32_e32 v157, 0xffff0000, v228
	v_lshlrev_b32_e32 v158, 16, v229
	v_and_b32_e32 v159, 0xffff0000, v229
	v_mul_f32_e32 v164, 0xbfb8aa3b, v156
	v_mul_f32_e32 v165, 0xbfb8aa3b, v157
	v_mul_f32_e32 v166, 0xbfb8aa3b, v158
	v_mul_f32_e32 v167, 0xbfb8aa3b, v159
	v_exp_f32_e32 v164, v164
	v_exp_f32_e32 v165, v165
	v_exp_f32_e32 v166, v166
	v_exp_f32_e32 v167, v167
	v_mul_f32_e32 v48, v48, v189
	v_mul_f32_e32 v49, v49, v189
	v_mul_f32_e32 v50, v50, v189
	v_mul_f32_e32 v51, v51, v189
	v_add_f32_e32 v164, 1.0, v164
	v_add_f32_e32 v165, 1.0, v165
	v_add_f32_e32 v166, 1.0, v166
	v_add_f32_e32 v167, 1.0, v167
	v_rcp_f32_e32 v164, v164
	v_rcp_f32_e32 v165, v165
	v_rcp_f32_e32 v166, v166
	v_rcp_f32_e32 v167, v167
	v_mul_f32_e32 v48, v48, v140
	v_mul_f32_e32 v49, v49, v141
	v_mul_f32_e32 v50, v50, v142
	v_mul_f32_e32 v51, v51, v143
	v_mul_f32_e32 v156, v156, v164
	v_mul_f32_e32 v157, v157, v165
	v_mul_f32_e32 v158, v158, v166
	v_mul_f32_e32 v159, v159, v167
	v_mul_f32_e32 v48, v48, v156
	v_mul_f32_e32 v49, v49, v157
	v_mul_f32_e32 v50, v50, v158
	v_mul_f32_e32 v51, v51, v159
	v_cvt_pk_bf16_f32 v228, v48, v49
	v_cvt_pk_bf16_f32 v229, v50, v51
	global_store_dwordx2 v199, v[228:229], s[54:55] offset:192
	v_lshlrev_b32_e32 v160, 16, v230
	v_and_b32_e32 v161, 0xffff0000, v230
	v_lshlrev_b32_e32 v162, 16, v231
	v_and_b32_e32 v163, 0xffff0000, v231
	v_mul_f32_e32 v168, 0xbfb8aa3b, v160
	v_mul_f32_e32 v169, 0xbfb8aa3b, v161
	v_mul_f32_e32 v170, 0xbfb8aa3b, v162
	v_mul_f32_e32 v171, 0xbfb8aa3b, v163
	v_exp_f32_e32 v168, v168
	v_exp_f32_e32 v169, v169
	v_exp_f32_e32 v170, v170
	v_exp_f32_e32 v171, v171
	v_mul_f32_e32 v52, v52, v189
	v_mul_f32_e32 v53, v53, v189
	v_mul_f32_e32 v54, v54, v189
	v_mul_f32_e32 v55, v55, v189
	v_add_f32_e32 v168, 1.0, v168
	v_add_f32_e32 v169, 1.0, v169
	v_add_f32_e32 v170, 1.0, v170
	v_add_f32_e32 v171, 1.0, v171
	v_rcp_f32_e32 v168, v168
	v_rcp_f32_e32 v169, v169
	v_rcp_f32_e32 v170, v170
	v_rcp_f32_e32 v171, v171
	v_mul_f32_e32 v52, v52, v144
	v_mul_f32_e32 v53, v53, v145
	v_mul_f32_e32 v54, v54, v146
	v_mul_f32_e32 v55, v55, v147
	v_mul_f32_e32 v160, v160, v168
	v_mul_f32_e32 v161, v161, v169
	v_mul_f32_e32 v162, v162, v170
	v_mul_f32_e32 v163, v163, v171
	v_mul_f32_e32 v52, v52, v160
	v_mul_f32_e32 v53, v53, v161
	v_mul_f32_e32 v54, v54, v162
	v_mul_f32_e32 v55, v55, v163
	v_cvt_pk_bf16_f32 v230, v52, v53
	v_cvt_pk_bf16_f32 v231, v54, v55
	global_store_dwordx2 v199, v[230:231], s[54:55] offset:208
	v_lshlrev_b32_e32 v156, 16, v232
	v_and_b32_e32 v157, 0xffff0000, v232
	v_lshlrev_b32_e32 v158, 16, v233
	v_and_b32_e32 v159, 0xffff0000, v233
	v_mul_f32_e32 v164, 0xbfb8aa3b, v156
	v_mul_f32_e32 v165, 0xbfb8aa3b, v157
	v_mul_f32_e32 v166, 0xbfb8aa3b, v158
	v_mul_f32_e32 v167, 0xbfb8aa3b, v159
	v_exp_f32_e32 v164, v164
	v_exp_f32_e32 v165, v165
	v_exp_f32_e32 v166, v166
	v_exp_f32_e32 v167, v167
	v_mul_f32_e32 v56, v56, v189
	v_mul_f32_e32 v57, v57, v189
	v_mul_f32_e32 v58, v58, v189
	v_mul_f32_e32 v59, v59, v189
	v_add_f32_e32 v164, 1.0, v164
	v_add_f32_e32 v165, 1.0, v165
	v_add_f32_e32 v166, 1.0, v166
	v_add_f32_e32 v167, 1.0, v167
	v_rcp_f32_e32 v164, v164
	v_rcp_f32_e32 v165, v165
	v_rcp_f32_e32 v166, v166
	v_rcp_f32_e32 v167, v167
	v_mul_f32_e32 v56, v56, v148
	v_mul_f32_e32 v57, v57, v149
	v_mul_f32_e32 v58, v58, v150
	v_mul_f32_e32 v59, v59, v151
	v_mul_f32_e32 v156, v156, v164
	v_mul_f32_e32 v157, v157, v165
	v_mul_f32_e32 v158, v158, v166
	v_mul_f32_e32 v159, v159, v167
	v_mul_f32_e32 v56, v56, v156
	v_mul_f32_e32 v57, v57, v157
	v_mul_f32_e32 v58, v58, v158
	v_mul_f32_e32 v59, v59, v159
	v_cvt_pk_bf16_f32 v232, v56, v57
	v_cvt_pk_bf16_f32 v233, v58, v59
	global_store_dwordx2 v199, v[232:233], s[54:55] offset:224
	v_lshlrev_b32_e32 v160, 16, v234
	v_and_b32_e32 v161, 0xffff0000, v234
	v_lshlrev_b32_e32 v162, 16, v235
	v_and_b32_e32 v163, 0xffff0000, v235
	v_mul_f32_e32 v168, 0xbfb8aa3b, v160
	v_mul_f32_e32 v169, 0xbfb8aa3b, v161
	v_mul_f32_e32 v170, 0xbfb8aa3b, v162
	v_mul_f32_e32 v171, 0xbfb8aa3b, v163
	v_exp_f32_e32 v168, v168
	v_exp_f32_e32 v169, v169
	v_exp_f32_e32 v170, v170
	v_exp_f32_e32 v171, v171
	v_mul_f32_e32 v60, v60, v189
	v_mul_f32_e32 v61, v61, v189
	v_mul_f32_e32 v62, v62, v189
	v_mul_f32_e32 v63, v63, v189
	v_add_f32_e32 v168, 1.0, v168
	v_add_f32_e32 v169, 1.0, v169
	v_add_f32_e32 v170, 1.0, v170
	v_add_f32_e32 v171, 1.0, v171
	v_rcp_f32_e32 v168, v168
	v_rcp_f32_e32 v169, v169
	v_rcp_f32_e32 v170, v170
	v_rcp_f32_e32 v171, v171
	v_mul_f32_e32 v60, v60, v152
	v_mul_f32_e32 v61, v61, v153
	v_mul_f32_e32 v62, v62, v154
	v_mul_f32_e32 v63, v63, v155
	v_mul_f32_e32 v160, v160, v168
	v_mul_f32_e32 v161, v161, v169
	v_mul_f32_e32 v162, v162, v170
	v_mul_f32_e32 v163, v163, v171
	v_mul_f32_e32 v60, v60, v160
	v_mul_f32_e32 v61, v61, v161
	v_mul_f32_e32 v62, v62, v162
	v_mul_f32_e32 v63, v63, v163
	v_cvt_pk_bf16_f32 v234, v60, v61
	v_cvt_pk_bf16_f32 v235, v62, v63
	global_store_dwordx2 v199, v[234:235], s[54:55] offset:240
	s_add_i32 s15, s15, 1
	s_cmp_lt_u32 s15, 2
	s_cbranch_scc1 .Laa_half
	s_add_i32 s14, s14, s18
	s_branch .Laa_unit
.Laa_done:
	s_cmpk_lt_i32 s2, 0x200
	s_cselect_b64 s[10:11], -1, 0
